# memory-attention units (both copies): LDS operand reads issued up to 4 steps ahead of their MFMAs with counted lgkmcnt waits (QK tiles 1-6, PV chains 2-4)
# speedup vs baseline: 1.0056x; 1.0056x over previous
.LBB0_547:
	s_ashr_i32 s38, s40, 7
	s_lshl_b32 s24, s38, 8
	s_add_i32 s42, s24, s30
	s_ashr_i32 s43, s42, 31
	s_lshl_b64 s[42:43], s[42:43], 10
	s_add_u32 s39, s22, s42
	s_addc_u32 s41, s23, s43
	s_and_b32 s24, s14, 0x180
	s_lshl_b32 s24, s24, 1
	s_add_u32 s44, s39, s24
	s_addc_u32 s45, s41, 0
	v_mov_b32_e32 v211, v208
	s_add_u32 s39, s31, s42
	s_addc_u32 s41, s21, s43
	s_waitcnt vmcnt(0)
	v_ashrrev_i32_e32 v62, 5, v211
	v_and_b32_e32 v69, -8, v62
	s_add_u32 s42, s39, s24
	v_and_b32_e32 v68, 0xff, v211
	v_lshlrev_b32_e32 v4, 3, v69
	s_addc_u32 s43, s41, 0
	v_lshlrev_b32_e32 v2, 10, v68
	v_ashrrev_i32_e32 v5, 31, v4
	v_or_b32_e32 v70, 1, v69
	v_lshl_add_u64 v[60:61], s[44:45], 0, v[2:3]
	v_lshl_add_u64 v[64:65], s[42:43], 0, v[2:3]
	v_lshlrev_b64 v[8:9], 1, v[4:5]
	v_lshlrev_b32_e32 v16, 3, v70
	v_or_b32_e32 v71, 2, v69
	v_or_b32_e32 v73, 4, v69
	v_lshl_add_u64 v[28:29], v[60:61], 0, v[8:9]
	v_lshl_add_u64 v[8:9], v[64:65], 0, v[8:9]
	v_ashrrev_i32_e32 v17, 31, v16
	v_lshlrev_b32_e32 v24, 3, v71
	v_or_b32_e32 v72, 3, v69
	v_lshlrev_b32_e32 v36, 3, v73
	global_load_dwordx4 v[4:7], v[28:29], off
	s_nop 0
	global_load_dwordx4 v[8:11], v[8:9], off
	s_nop 0
	global_load_dwordx4 v[12:15], v[28:29], off offset:16
	v_lshl_add_u64 v[16:17], v[16:17], 1, v[64:65]
	v_ashrrev_i32_e32 v25, 31, v24
	v_lshlrev_b32_e32 v32, 3, v72
	v_ashrrev_i32_e32 v37, 31, v36
	global_load_dwordx4 v[16:19], v[16:17], off
	s_nop 0
	global_load_dwordx4 v[20:23], v[28:29], off offset:32
	v_lshl_add_u64 v[24:25], v[24:25], 1, v[64:65]
	v_ashrrev_i32_e32 v33, 31, v32
	v_lshlrev_b64 v[40:41], 1, v[36:37]
	v_or_b32_e32 v74, 5, v69
	v_or_b32_e32 v75, 6, v69
	v_or_b32_e32 v76, 7, v62
	global_load_dwordx4 v[24:27], v[24:25], off
	s_nop 0
	global_load_dwordx4 v[28:31], v[28:29], off offset:48
	v_lshl_add_u64 v[32:33], v[32:33], 1, v[64:65]
	v_lshl_add_u64 v[52:53], v[60:61], 0, v[40:41]
	v_lshlrev_b32_e32 v48, 3, v74
	v_lshlrev_b32_e32 v56, 3, v75
	v_lshlrev_b32_e32 v62, 3, v76
	global_load_dwordx4 v[32:35], v[32:33], off
	v_lshl_add_u64 v[40:41], v[64:65], 0, v[40:41]
	global_load_dwordx4 v[36:39], v[52:53], off
	v_ashrrev_i32_e32 v49, 31, v48
	v_ashrrev_i32_e32 v57, 31, v56
	v_ashrrev_i32_e32 v63, 31, v62
	global_load_dwordx4 v[40:43], v[40:41], off
	v_lshl_add_u64 v[48:49], v[48:49], 1, v[64:65]
	global_load_dwordx4 v[44:47], v[52:53], off offset:16
	v_lshl_add_u64 v[56:57], v[56:57], 1, v[64:65]
	v_lshlrev_b64 v[66:67], 1, v[62:63]
	global_load_dwordx4 v[48:51], v[48:49], off
	v_lshl_add_u64 v[60:61], v[60:61], 0, v[66:67]
	global_load_dwordx4 v[56:59], v[56:57], off
	v_lshl_add_u64 v[64:65], v[64:65], 0, v[66:67]
	global_load_dwordx4 v[52:55], v[52:53], off offset:32
	v_mad_u32_u24 v77, v68, s53, 0
	global_load_dwordx4 v[60:63], v[60:61], off
	v_lshl_add_u32 v2, v68, 1, s11
	global_load_dwordx4 v[64:67], v[64:65], off
	v_lshl_add_u32 v78, v69, 4, v77
	v_mad_u64_u32 v[68:69], s[42:43], v69, s77, v[2:3]
	v_lshl_add_u32 v69, v70, 4, v77
	s_ashr_i32 s39, s38, 31
	s_lshl_b64 s[38:39], s[38:39], 13
	s_and_b32 s41, s1, 0x1f00
	s_add_u32 s41, s41, s3
	v_and_b32_e32 v213, 31, v211
	v_bfe_u32 v201, v211, 4, 2
	s_waitcnt vmcnt(15)
	ds_write_b128 v78, v[4:7]
	s_waitcnt vmcnt(14)
	ds_write_b16 v68, v8
	ds_write_b16_d16_hi v68, v8 offset:520
	ds_write_b16 v68, v9 offset:1040
	ds_write_b16_d16_hi v68, v9 offset:1560
	ds_write_b16 v68, v10 offset:2080
	ds_write_b16_d16_hi v68, v10 offset:2600
	ds_write_b16 v68, v11 offset:3120
	ds_write_b16_d16_hi v68, v11 offset:3640
	s_waitcnt vmcnt(13)
	ds_write_b128 v69, v[12:15]
	s_waitcnt vmcnt(12)
	ds_write_b16 v68, v16 offset:4160
	ds_write_b16_d16_hi v68, v16 offset:4680
	ds_write_b16 v68, v17 offset:5200
	ds_write_b16_d16_hi v68, v17 offset:5720
	ds_write_b16 v68, v18 offset:6240
	ds_write_b16_d16_hi v68, v18 offset:6760
	ds_write_b16 v68, v19 offset:7280
	ds_write_b16_d16_hi v68, v19 offset:7800
	v_lshl_add_u32 v4, v71, 4, v77
	s_waitcnt vmcnt(11)
	ds_write_b128 v4, v[20:23]
	s_waitcnt vmcnt(10)
	ds_write_b16 v68, v24 offset:8320
	ds_write_b16_d16_hi v68, v24 offset:8840
	ds_write_b16 v68, v25 offset:9360
	ds_write_b16_d16_hi v68, v25 offset:9880
	ds_write_b16 v68, v26 offset:10400
	ds_write_b16_d16_hi v68, v26 offset:10920
	ds_write_b16 v68, v27 offset:11440
	ds_write_b16_d16_hi v68, v27 offset:11960
	v_lshl_add_u32 v4, v72, 4, v77
	s_waitcnt vmcnt(9)
	ds_write_b128 v4, v[28:31]
	s_waitcnt vmcnt(8)
	ds_write_b16 v68, v32 offset:12480
	ds_write_b16_d16_hi v68, v32 offset:13000
	ds_write_b16 v68, v33 offset:13520
	ds_write_b16_d16_hi v68, v33 offset:14040
	ds_write_b16 v68, v34 offset:14560
	ds_write_b16_d16_hi v68, v34 offset:15080
	ds_write_b16 v68, v35 offset:15600
	ds_write_b16_d16_hi v68, v35 offset:16120
	v_lshl_add_u32 v4, v73, 4, v77
	s_waitcnt vmcnt(7)
	ds_write_b128 v4, v[36:39]
	s_waitcnt vmcnt(6)
	ds_write_b16 v68, v40 offset:16640
	ds_write_b16_d16_hi v68, v40 offset:17160
	ds_write_b16 v68, v41 offset:17680
	ds_write_b16_d16_hi v68, v41 offset:18200
	ds_write_b16 v68, v42 offset:18720
	ds_write_b16_d16_hi v68, v42 offset:19240
	ds_write_b16 v68, v43 offset:19760
	ds_write_b16_d16_hi v68, v43 offset:20280
	v_lshl_add_u32 v4, v74, 4, v77
	s_waitcnt vmcnt(5)
	ds_write_b128 v4, v[44:47]
	s_waitcnt vmcnt(4)
	ds_write_b16 v68, v48 offset:20800
	ds_write_b16_d16_hi v68, v48 offset:21320
	ds_write_b16 v68, v49 offset:21840
	ds_write_b16_d16_hi v68, v49 offset:22360
	ds_write_b16 v68, v50 offset:22880
	ds_write_b16_d16_hi v68, v50 offset:23400
	ds_write_b16 v68, v51 offset:23920
	ds_write_b16_d16_hi v68, v51 offset:24440
	v_lshl_add_u32 v4, v75, 4, v77
	s_waitcnt vmcnt(2)
	ds_write_b128 v4, v[52:55]
	ds_write_b16 v68, v56 offset:24960
	ds_write_b16_d16_hi v68, v56 offset:25480
	ds_write_b16 v68, v57 offset:26000
	ds_write_b16_d16_hi v68, v57 offset:26520
	ds_write_b16 v68, v58 offset:27040
	ds_write_b16_d16_hi v68, v58 offset:27560
	ds_write_b16 v68, v59 offset:28080
	ds_write_b16_d16_hi v68, v59 offset:28600
	v_lshl_add_u32 v4, v76, 4, v77
	s_waitcnt vmcnt(1)
	ds_write_b128 v4, v[60:63]
	v_mad_u64_u32 v[4:5], s[42:43], v76, s77, v[2:3]
	s_addc_u32 s42, 0, s20
	s_add_u32 s38, s41, s38
	s_waitcnt vmcnt(0)
	ds_write_b16 v4, v64
	ds_write_b16_d16_hi v4, v64 offset:520
	ds_write_b16 v4, v65 offset:1040
	ds_write_b16_d16_hi v4, v65 offset:1560
	ds_write_b16 v4, v66 offset:2080
	ds_write_b16_d16_hi v4, v66 offset:2600
	ds_write_b16 v4, v67 offset:3120
	ds_write_b16_d16_hi v4, v67 offset:3640
	v_or_b32_e32 v2, s38, v213
	v_mov_b64_e32 v[4:5], s[72:73]
	s_addc_u32 s39, s42, s39
	v_mad_u64_u32 v[4:5], s[42:43], v2, s16, v[4:5]
	v_lshrrev_b32_e32 v2, 2, v211
	v_mad_i32_i24 v5, s39, v238, v5
	v_and_b32_e32 v215, 8, v2
	v_lshl_add_u64 v[4:5], v[4:5], 0, s[24:25]
	v_lshlrev_b32_e32 v6, 1, v215
	v_mov_b32_e32 v7, v3
	v_lshl_add_u64 v[4:5], v[4:5], 0, v[6:7]
	v_add_co_u32_e32 v6, vcc, s17, v4
	s_waitcnt lgkmcnt(0)
	s_nop 0
	v_addc_co_u32_e32 v7, vcc, 0, v5, vcc
	s_barrier
	global_load_dwordx4 v[116:119], v[6:7], off
	v_lshl_add_u64 v[8:9], v[4:5], 0, s[64:65]
	global_load_dwordx4 v[188:191], v[8:9], off offset:32
	global_load_dwordx4 v[184:187], v[8:9], off offset:64
	global_load_dwordx4 v[180:183], v[8:9], off offset:96
	global_load_dwordx4 v[176:179], v[8:9], off offset:128
	global_load_dwordx4 v[168:171], v[8:9], off offset:160
	global_load_dwordx4 v[164:167], v[8:9], off offset:192
	s_mul_i32 s41, s39, 0x1800
	s_mul_hi_u32 s42, s38, 0x1800
	s_add_i32 s42, s42, s41
	s_mul_i32 s41, s38, 0x1800
	v_lshrrev_b32_e32 v2, 1, v211
	s_add_u32 s41, s72, s41
	v_and_b32_e32 v2, 16, v2
	v_mul_u32_u24_e32 v4, 0x110, v213
	s_addc_u32 s43, s73, s42
	v_add3_u32 v202, 0, v2, v4
	s_add_u32 s42, s41, s24
	v_mul_u32_u24_e32 v2, 0xc00, v201
	s_addc_u32 s43, s43, 0
	v_lshlrev_b32_e32 v2, 1, v2
	global_load_dwordx4 v[172:175], v[8:9], off offset:224
	v_lshl_add_u64 v[8:9], s[42:43], 0, v[2:3]
	v_lshlrev_b32_e32 v2, 4, v211
	v_and_b32_e32 v2, 0xf0, v2
	v_lshl_add_u64 v[8:9], v[8:9], 0, v[2:3]
	v_add_co_u32_e32 v10, vcc, s17, v8
	ds_read_b128 v[4:7], v202
	s_nop 0
	v_addc_co_u32_e32 v11, vcc, 0, v9, vcc
	v_add_co_u32_e32 v12, vcc, s51, v8
	s_nop 1
	v_addc_co_u32_e32 v13, vcc, 0, v9, vcc
	global_load_dwordx4 v[160:163], v[10:11], off offset:1024
	global_load_dwordx4 v[156:159], v[12:13], off offset:1024
	v_add_co_u32_e32 v10, vcc, s58, v8
	s_nop 1
	v_addc_co_u32_e32 v11, vcc, 0, v9, vcc
	v_add_co_u32_e32 v12, vcc, s59, v8
	s_nop 1
	v_addc_co_u32_e32 v13, vcc, 0, v9, vcc
	global_load_dwordx4 v[152:155], v[10:11], off offset:1024
	global_load_dwordx4 v[148:151], v[12:13], off offset:1024
	v_add_co_u32_e32 v10, vcc, s60, v8
	s_nop 1
	v_addc_co_u32_e32 v11, vcc, 0, v9, vcc
	v_add_co_u32_e32 v12, vcc, s61, v8
	s_nop 1
	v_addc_co_u32_e32 v13, vcc, 0, v9, vcc
	global_load_dwordx4 v[144:147], v[10:11], off offset:1024
	global_load_dwordx4 v[140:143], v[12:13], off offset:1024
	v_add_co_u32_e32 v10, vcc, s63, v8
	s_nop 1
	v_addc_co_u32_e32 v11, vcc, 0, v9, vcc
	v_add_co_u32_e32 v8, vcc, s46, v8
	s_nop 1
	v_addc_co_u32_e32 v9, vcc, 0, v9, vcc
	global_load_dwordx4 v[136:139], v[10:11], off offset:1024
	global_load_dwordx4 v[132:135], v[8:9], off offset:1024
	ds_read_b128 v[20:23], v202 offset:32
	s_waitcnt vmcnt(15) lgkmcnt(1)
	v_mfma_f32_32x32x16_bf16 v[4:19], v[4:7], v[116:119], 0
	s_waitcnt vmcnt(14) lgkmcnt(0)
	v_mfma_f32_32x32x16_bf16 v[4:19], v[20:23], v[188:191], v[4:19]
	ds_read_b128 v[20:23], v202 offset:64
	s_waitcnt vmcnt(13) lgkmcnt(0)
	v_mfma_f32_32x32x16_bf16 v[4:19], v[20:23], v[184:187], v[4:19]
	ds_read_b128 v[20:23], v202 offset:96
	s_waitcnt vmcnt(12) lgkmcnt(0)
	v_mfma_f32_32x32x16_bf16 v[4:19], v[20:23], v[180:183], v[4:19]
	ds_read_b128 v[20:23], v202 offset:128
	s_waitcnt vmcnt(11) lgkmcnt(0)
	v_mfma_f32_32x32x16_bf16 v[4:19], v[20:23], v[176:179], v[4:19]
	ds_read_b128 v[20:23], v202 offset:160
	s_waitcnt vmcnt(10) lgkmcnt(0)
	v_mfma_f32_32x32x16_bf16 v[4:19], v[20:23], v[168:171], v[4:19]
	ds_read_b128 v[20:23], v202 offset:192
	s_waitcnt vmcnt(9) lgkmcnt(0)
	v_mfma_f32_32x32x16_bf16 v[4:19], v[20:23], v[164:167], v[4:19]
	ds_read_b128 v[20:23], v202 offset:224
	s_waitcnt vmcnt(8) lgkmcnt(0)
	v_mfma_f32_32x32x16_bf16 v[4:19], v[20:23], v[172:175], v[4:19]
	ds_read_b128 v[20:23], v202 offset:8704
	ds_read_b128 v[36:39], v202 offset:8736
	ds_read_b128 v[40:43], v202 offset:8768
	ds_read_b128 v[44:47], v202 offset:8800
	ds_read_b128 v[48:51], v202 offset:8832
	s_waitcnt lgkmcnt(4)
	v_mfma_f32_32x32x16_bf16 v[20:35], v[20:23], v[116:119], 0
	s_waitcnt lgkmcnt(3)
	v_mfma_f32_32x32x16_bf16 v[20:35], v[36:39], v[188:191], v[20:35]
	ds_read_b128 v[36:39], v202 offset:8864
	s_waitcnt lgkmcnt(3)
	v_mfma_f32_32x32x16_bf16 v[20:35], v[40:43], v[184:187], v[20:35]
	ds_read_b128 v[40:43], v202 offset:8896
	s_waitcnt lgkmcnt(3)
	v_mfma_f32_32x32x16_bf16 v[20:35], v[44:47], v[180:183], v[20:35]
	ds_read_b128 v[44:47], v202 offset:8928
	s_waitcnt lgkmcnt(3)
	v_mfma_f32_32x32x16_bf16 v[20:35], v[48:51], v[176:179], v[20:35]
	s_waitcnt lgkmcnt(2)
	v_mfma_f32_32x32x16_bf16 v[20:35], v[36:39], v[168:171], v[20:35]
	s_waitcnt lgkmcnt(1)
	v_mfma_f32_32x32x16_bf16 v[20:35], v[40:43], v[164:167], v[20:35]
	s_waitcnt lgkmcnt(0)
	v_mfma_f32_32x32x16_bf16 v[20:35], v[44:47], v[172:175], v[20:35]
	ds_read_b128 v[36:39], v202 offset:17408
	ds_read_b128 v[52:55], v202 offset:17440
	ds_read_b128 v[56:59], v202 offset:17472
	ds_read_b128 v[60:63], v202 offset:17504
	ds_read_b128 v[64:67], v202 offset:17536
	v_or_b32_e32 v214, 64, v213
	s_waitcnt lgkmcnt(4)
	v_mfma_f32_32x32x16_bf16 v[36:51], v[36:39], v[116:119], 0
	s_waitcnt lgkmcnt(3)
	v_mfma_f32_32x32x16_bf16 v[36:51], v[52:55], v[188:191], v[36:51]
	ds_read_b128 v[52:55], v202 offset:17568
	s_waitcnt lgkmcnt(3)
	v_mfma_f32_32x32x16_bf16 v[36:51], v[56:59], v[184:187], v[36:51]
	ds_read_b128 v[56:59], v202 offset:17600
	s_waitcnt lgkmcnt(3)
	v_mfma_f32_32x32x16_bf16 v[36:51], v[60:63], v[180:183], v[36:51]
	ds_read_b128 v[60:63], v202 offset:17632
	s_waitcnt lgkmcnt(3)
	v_mfma_f32_32x32x16_bf16 v[36:51], v[64:67], v[176:179], v[36:51]
	s_waitcnt lgkmcnt(2)
	v_mfma_f32_32x32x16_bf16 v[36:51], v[52:55], v[168:171], v[36:51]
	s_waitcnt lgkmcnt(1)
	v_mfma_f32_32x32x16_bf16 v[36:51], v[56:59], v[164:167], v[36:51]
	s_waitcnt lgkmcnt(0)
	v_mfma_f32_32x32x16_bf16 v[36:51], v[60:63], v[172:175], v[36:51]
	ds_read_b128 v[52:55], v202 offset:26112
	ds_read_b128 v[68:71], v202 offset:26144
	ds_read_b128 v[72:75], v202 offset:26176
	ds_read_b128 v[76:79], v202 offset:26208
	ds_read_b128 v[80:83], v202 offset:26240
	v_or_b32_e32 v212, 0x60, v213
	s_waitcnt lgkmcnt(4)
	v_mfma_f32_32x32x16_bf16 v[52:67], v[52:55], v[116:119], 0
	s_waitcnt lgkmcnt(3)
	v_mfma_f32_32x32x16_bf16 v[52:67], v[68:71], v[188:191], v[52:67]
	ds_read_b128 v[68:71], v202 offset:26272
	s_waitcnt lgkmcnt(3)
	v_mfma_f32_32x32x16_bf16 v[52:67], v[72:75], v[184:187], v[52:67]
	ds_read_b128 v[72:75], v202 offset:26304
	s_waitcnt lgkmcnt(3)
	v_mfma_f32_32x32x16_bf16 v[52:67], v[76:79], v[180:183], v[52:67]
	ds_read_b128 v[76:79], v202 offset:26336
	s_waitcnt lgkmcnt(3)
	v_mfma_f32_32x32x16_bf16 v[52:67], v[80:83], v[176:179], v[52:67]
	s_waitcnt lgkmcnt(2)
	v_mfma_f32_32x32x16_bf16 v[52:67], v[68:71], v[168:171], v[52:67]
	s_waitcnt lgkmcnt(1)
	v_mfma_f32_32x32x16_bf16 v[52:67], v[72:75], v[164:167], v[52:67]
	s_waitcnt lgkmcnt(0)
	v_mfma_f32_32x32x16_bf16 v[52:67], v[76:79], v[172:175], v[52:67]
	ds_read_b128 v[68:71], v202 offset:34816
	ds_read_b128 v[84:87], v202 offset:34848
	ds_read_b128 v[88:91], v202 offset:34880
	ds_read_b128 v[92:95], v202 offset:34912
	ds_read_b128 v[96:99], v202 offset:34944
	s_waitcnt lgkmcnt(4)
	v_mfma_f32_32x32x16_bf16 v[68:83], v[68:71], v[116:119], 0
	s_waitcnt lgkmcnt(3)
	v_mfma_f32_32x32x16_bf16 v[68:83], v[84:87], v[188:191], v[68:83]
	ds_read_b128 v[84:87], v202 offset:34976
	s_waitcnt lgkmcnt(3)
	v_mfma_f32_32x32x16_bf16 v[68:83], v[88:91], v[184:187], v[68:83]
	ds_read_b128 v[88:91], v202 offset:35008
	s_waitcnt lgkmcnt(3)
	v_mfma_f32_32x32x16_bf16 v[68:83], v[92:95], v[180:183], v[68:83]
	ds_read_b128 v[92:95], v202 offset:35040
	s_waitcnt lgkmcnt(3)
	v_mfma_f32_32x32x16_bf16 v[68:83], v[96:99], v[176:179], v[68:83]
	s_waitcnt lgkmcnt(2)
	v_mfma_f32_32x32x16_bf16 v[68:83], v[84:87], v[168:171], v[68:83]
	s_waitcnt lgkmcnt(1)
	v_mfma_f32_32x32x16_bf16 v[68:83], v[88:91], v[164:167], v[68:83]
	s_waitcnt lgkmcnt(0)
	v_mfma_f32_32x32x16_bf16 v[68:83], v[92:95], v[172:175], v[68:83]
	ds_read_b128 v[84:87], v202 offset:43520
	ds_read_b128 v[100:103], v202 offset:43552
	ds_read_b128 v[104:107], v202 offset:43584
	ds_read_b128 v[108:111], v202 offset:43616
	ds_read_b128 v[112:115], v202 offset:43648
	s_waitcnt lgkmcnt(4)
	v_mfma_f32_32x32x16_bf16 v[84:99], v[84:87], v[116:119], 0
	s_waitcnt lgkmcnt(3)
	v_mfma_f32_32x32x16_bf16 v[84:99], v[100:103], v[188:191], v[84:99]
	ds_read_b128 v[100:103], v202 offset:43680
	s_waitcnt lgkmcnt(3)
	v_mfma_f32_32x32x16_bf16 v[84:99], v[104:107], v[184:187], v[84:99]
	ds_read_b128 v[104:107], v202 offset:43712
	s_waitcnt lgkmcnt(3)
	v_mfma_f32_32x32x16_bf16 v[84:99], v[108:111], v[180:183], v[84:99]
	ds_read_b128 v[108:111], v202 offset:43744
	s_waitcnt lgkmcnt(3)
	v_mfma_f32_32x32x16_bf16 v[84:99], v[112:115], v[176:179], v[84:99]
	s_waitcnt lgkmcnt(2)
	v_mfma_f32_32x32x16_bf16 v[84:99], v[100:103], v[168:171], v[84:99]
	s_waitcnt lgkmcnt(1)
	v_mfma_f32_32x32x16_bf16 v[84:99], v[104:107], v[164:167], v[84:99]
	s_waitcnt lgkmcnt(0)
	v_mfma_f32_32x32x16_bf16 v[84:99], v[108:111], v[172:175], v[84:99]
	ds_read_b128 v[100:103], v202 offset:52224
	ds_read_b128 v[120:123], v202 offset:52256
	ds_read_b128 v[124:127], v202 offset:52288
	ds_read_b128 v[128:131], v202 offset:52320
	s_waitcnt lgkmcnt(3)
	v_mfma_f32_32x32x16_bf16 v[100:115], v[100:103], v[116:119], 0
	s_waitcnt lgkmcnt(2)
	v_mfma_f32_32x32x16_bf16 v[100:115], v[120:123], v[188:191], v[100:115]
	ds_read_b128 v[120:123], v202 offset:52352
	s_waitcnt lgkmcnt(2)
	v_mfma_f32_32x32x16_bf16 v[100:115], v[124:127], v[184:187], v[100:115]
	ds_read_b128 v[124:127], v202 offset:52384
	s_waitcnt lgkmcnt(2)
	v_mfma_f32_32x32x16_bf16 v[100:115], v[128:131], v[180:183], v[100:115]
	ds_read_b128 v[128:131], v202 offset:52416
	s_waitcnt lgkmcnt(2)
	v_mfma_f32_32x32x16_bf16 v[100:115], v[120:123], v[176:179], v[100:115]
	ds_read_b128 v[120:123], v202 offset:52448
	s_waitcnt lgkmcnt(2)
	v_mfma_f32_32x32x16_bf16 v[100:115], v[124:127], v[168:171], v[100:115]
	s_waitcnt lgkmcnt(1)
	v_mfma_f32_32x32x16_bf16 v[100:115], v[128:131], v[164:167], v[100:115]
	s_waitcnt lgkmcnt(0)
	v_mfma_f32_32x32x16_bf16 v[100:115], v[120:123], v[172:175], v[100:115]
	ds_read_b128 v[120:123], v202 offset:60928
	ds_read_b128 v[204:207], v202 offset:60960
	s_waitcnt lgkmcnt(1)
	v_mfma_f32_32x32x16_bf16 v[116:131], v[120:123], v[116:119], 0
	s_waitcnt lgkmcnt(0)
	v_mfma_f32_32x32x16_bf16 v[116:131], v[204:207], v[188:191], v[116:131]
	ds_read_b128 v[188:191], v202 offset:60992
	s_waitcnt lgkmcnt(0)
	v_mfma_f32_32x32x16_bf16 v[116:131], v[188:191], v[184:187], v[116:131]
	ds_read_b128 v[184:187], v202 offset:61024
	s_waitcnt lgkmcnt(0)
	v_mfma_f32_32x32x16_bf16 v[116:131], v[184:187], v[180:183], v[116:131]
	ds_read_b128 v[180:183], v202 offset:61056
	s_waitcnt lgkmcnt(0)
	v_mfma_f32_32x32x16_bf16 v[116:131], v[180:183], v[176:179], v[116:131]
	ds_read_b128 v[176:179], v202 offset:61088
	s_waitcnt lgkmcnt(0)
	v_mfma_f32_32x32x16_bf16 v[116:131], v[176:179], v[168:171], v[116:131]
	ds_read_b128 v[168:171], v202 offset:61120
	s_waitcnt lgkmcnt(0)
	v_mfma_f32_32x32x16_bf16 v[116:131], v[168:171], v[164:167], v[116:131]
	ds_read_b128 v[164:167], v202 offset:61152
	s_waitcnt lgkmcnt(0)
	v_mfma_f32_32x32x16_bf16 v[116:131], v[164:167], v[172:175], v[116:131]
	v_max3_f32 v164, v4, s76, v5
	v_max3_f32 v164, v164, v6, v7
	v_max3_f32 v164, v164, v8, v9
	v_max3_f32 v164, v164, v10, v11
	v_max3_f32 v164, v164, v12, v13
	v_max3_f32 v164, v164, v14, v15
	v_max3_f32 v164, v164, v16, v17
	v_max3_f32 v164, v164, v18, v19
	v_max3_f32 v164, v164, v20, v21
	v_max3_f32 v164, v164, v22, v23
	v_max3_f32 v164, v164, v24, v25
	v_max3_f32 v164, v164, v26, v27
	v_max3_f32 v164, v164, v28, v29
	v_max3_f32 v164, v164, v30, v31
	v_max3_f32 v164, v164, v32, v33
	v_max3_f32 v164, v164, v34, v35
	v_max3_f32 v164, v164, v36, v37
	v_max3_f32 v164, v164, v38, v39
	v_max3_f32 v164, v164, v40, v41
	v_max3_f32 v164, v164, v42, v43
	v_max3_f32 v164, v164, v44, v45
	v_max3_f32 v164, v164, v46, v47
	v_max3_f32 v164, v164, v48, v49
	v_max3_f32 v164, v164, v50, v51
	v_max3_f32 v164, v164, v52, v53
	v_max3_f32 v164, v164, v54, v55
	v_max3_f32 v164, v164, v56, v57
	v_max3_f32 v164, v164, v58, v59
	v_max3_f32 v164, v164, v60, v61
	v_max3_f32 v164, v164, v62, v63
	v_max3_f32 v164, v164, v64, v65
	v_max3_f32 v164, v164, v66, v67
	v_max3_f32 v164, v164, v68, v69
	v_max3_f32 v164, v164, v70, v71
	v_max3_f32 v164, v164, v72, v73
	v_max3_f32 v164, v164, v74, v75
	v_max3_f32 v164, v164, v76, v77
	v_max3_f32 v164, v164, v78, v79
	v_max3_f32 v164, v164, v80, v81
	v_max3_f32 v164, v164, v82, v83
	v_max3_f32 v164, v164, v84, v85
	v_max3_f32 v164, v164, v86, v87
	v_max3_f32 v164, v164, v88, v89
	v_max3_f32 v164, v164, v90, v91
	v_max3_f32 v164, v164, v92, v93
	v_max3_f32 v164, v164, v94, v95
	v_max3_f32 v164, v164, v96, v97
	v_max3_f32 v164, v164, v98, v99
	v_max3_f32 v164, v164, v100, v101
	v_max3_f32 v164, v164, v102, v103
	v_max3_f32 v164, v164, v104, v105
	v_max3_f32 v164, v164, v106, v107
	v_max3_f32 v164, v164, v108, v109
	v_max3_f32 v164, v164, v110, v111
	v_max3_f32 v164, v164, v112, v113
	v_max3_f32 v164, v164, v114, v115
	v_max3_f32 v164, v164, v116, v117
	v_max3_f32 v164, v164, v118, v119
	v_max3_f32 v164, v164, v120, v121
	v_max3_f32 v164, v164, v122, v123
	v_max3_f32 v164, v164, v124, v125
	v_max3_f32 v164, v164, v126, v127
	v_cmp_lt_i32_e32 vcc, v236, v235
	v_max3_f32 v164, v164, v128, v129
	v_max3_f32 v164, v164, v130, v131
	v_cndmask_b32_e32 v165, v231, v236, vcc
	v_lshlrev_b32_e32 v216, 2, v165
	ds_bpermute_b32 v165, v216, v164
	s_waitcnt lgkmcnt(0)
	s_barrier
	v_max_f32_e32 v165, v165, v165
	v_max_f32_e32 v217, v164, v165
	v_sub_f32_e32 v10, v10, v217
	v_exp_f32_e32 v164, v10
	v_sub_f32_e32 v10, v11, v217
	v_exp_f32_e32 v165, v10
	v_sub_f32_e32 v10, v12, v217
	v_exp_f32_e32 v166, v10
	v_sub_f32_e32 v10, v13, v217
	v_exp_f32_e32 v167, v10
	v_sub_f32_e32 v10, v14, v217
	v_exp_f32_e32 v168, v10
	v_sub_f32_e32 v10, v15, v217
	v_exp_f32_e32 v169, v10
	v_sub_f32_e32 v10, v16, v217
	v_exp_f32_e32 v170, v10
	v_sub_f32_e32 v10, v17, v217
	v_sub_f32_e32 v16, v26, v217
	v_exp_f32_e32 v171, v10
	v_sub_f32_e32 v10, v18, v217
	v_exp_f32_e32 v18, v16
	v_sub_f32_e32 v16, v27, v217
	v_exp_f32_e32 v172, v10
	v_sub_f32_e32 v10, v19, v217
	v_exp_f32_e32 v19, v16
	v_sub_f32_e32 v16, v28, v217
	v_exp_f32_e32 v28, v16
	v_sub_f32_e32 v16, v29, v217
	v_exp_f32_e32 v29, v16
	v_sub_f32_e32 v16, v30, v217
	v_exp_f32_e32 v30, v16
	v_sub_f32_e32 v16, v31, v217
	v_exp_f32_e32 v31, v16
	v_sub_f32_e32 v16, v32, v217
	v_exp_f32_e32 v32, v16
	v_sub_f32_e32 v16, v33, v217
	v_exp_f32_e32 v33, v16
	v_sub_f32_e32 v16, v34, v217
	v_exp_f32_e32 v173, v10
	v_sub_f32_e32 v10, v20, v217
	v_exp_f32_e32 v34, v16
	v_sub_f32_e32 v16, v35, v217
	v_sub_f32_e32 v20, v38, v217
	v_exp_f32_e32 v35, v16
	v_sub_f32_e32 v16, v36, v217
	v_exp_f32_e32 v36, v20
	v_sub_f32_e32 v20, v39, v217
	v_sub_f32_e32 v17, v37, v217
	v_exp_f32_e32 v37, v20
	v_sub_f32_e32 v20, v40, v217
	v_exp_f32_e32 v38, v20
	v_sub_f32_e32 v20, v41, v217
	v_exp_f32_e32 v39, v20
	v_sub_f32_e32 v20, v42, v217
	v_exp_f32_e32 v40, v20
	v_sub_f32_e32 v20, v43, v217
	v_exp_f32_e32 v41, v20
	v_sub_f32_e32 v20, v44, v217
	v_exp_f32_e32 v42, v20
	v_sub_f32_e32 v20, v45, v217
	v_exp_f32_e32 v43, v20
	v_sub_f32_e32 v20, v46, v217
	v_exp_f32_e32 v174, v20
	v_sub_f32_e32 v20, v47, v217
	v_exp_f32_e32 v175, v20
	v_sub_f32_e32 v20, v48, v217
	v_exp_f32_e32 v176, v20
	v_sub_f32_e32 v20, v49, v217
	v_exp_f32_e32 v177, v20
	v_sub_f32_e32 v20, v50, v217
	v_exp_f32_e32 v178, v20
	v_sub_f32_e32 v20, v51, v217
	v_exp_f32_e32 v179, v20
	v_sub_f32_e32 v20, v52, v217
	v_exp_f32_e32 v44, v20
	v_sub_f32_e32 v20, v53, v217
	v_exp_f32_e32 v45, v20
	v_sub_f32_e32 v20, v54, v217
	v_exp_f32_e32 v46, v20
	v_sub_f32_e32 v20, v55, v217
	v_exp_f32_e32 v47, v20
	v_sub_f32_e32 v20, v56, v217
	v_exp_f32_e32 v48, v20
	v_sub_f32_e32 v20, v57, v217
	v_exp_f32_e32 v49, v20
	v_sub_f32_e32 v20, v58, v217
	v_exp_f32_e32 v50, v20
	v_sub_f32_e32 v20, v59, v217
	v_exp_f32_e32 v51, v20
	v_sub_f32_e32 v20, v60, v217
	v_exp_f32_e32 v56, v20
	v_sub_f32_e32 v20, v61, v217
	v_exp_f32_e32 v57, v20
	v_sub_f32_e32 v20, v62, v217
	v_exp_f32_e32 v60, v20
	v_sub_f32_e32 v20, v63, v217
	v_exp_f32_e32 v61, v20
	v_sub_f32_e32 v20, v64, v217
	v_exp_f32_e32 v180, v20
	v_sub_f32_e32 v20, v65, v217
	v_exp_f32_e32 v181, v20
	v_sub_f32_e32 v20, v66, v217
	v_exp_f32_e32 v182, v20
	v_sub_f32_e32 v20, v67, v217
	v_exp_f32_e32 v183, v20
	v_sub_f32_e32 v20, v68, v217
	v_exp_f32_e32 v52, v20
	v_sub_f32_e32 v20, v69, v217
	v_exp_f32_e32 v53, v20
	v_sub_f32_e32 v20, v70, v217
	v_exp_f32_e32 v54, v20
	v_sub_f32_e32 v20, v71, v217
	v_exp_f32_e32 v55, v20
	v_sub_f32_e32 v20, v72, v217
	v_exp_f32_e32 v58, v20
	v_sub_f32_e32 v20, v73, v217
	v_exp_f32_e32 v59, v20
	v_sub_f32_e32 v20, v74, v217
	v_exp_f32_e32 v64, v20
	v_sub_f32_e32 v20, v75, v217
	v_exp_f32_e32 v65, v20
	v_sub_f32_e32 v20, v76, v217
	v_exp_f32_e32 v68, v20
	v_sub_f32_e32 v20, v77, v217
	v_exp_f32_e32 v69, v20
	v_sub_f32_e32 v20, v78, v217
	v_exp_f32_e32 v72, v20
	v_sub_f32_e32 v20, v79, v217
	v_exp_f32_e32 v73, v20
	v_sub_f32_e32 v20, v80, v217
	v_exp_f32_e32 v186, v20
	v_sub_f32_e32 v20, v81, v217
	v_exp_f32_e32 v187, v20
	v_sub_f32_e32 v20, v82, v217
	v_exp_f32_e32 v190, v20
	v_sub_f32_e32 v20, v83, v217
	v_exp_f32_e32 v191, v20
	v_sub_f32_e32 v20, v84, v217
	v_exp_f32_e32 v62, v20
	v_sub_f32_e32 v20, v85, v217
	v_exp_f32_e32 v63, v20
	v_sub_f32_e32 v20, v86, v217
	v_exp_f32_e32 v66, v20
	v_sub_f32_e32 v20, v87, v217
	v_exp_f32_e32 v67, v20
	v_sub_f32_e32 v20, v88, v217
	v_exp_f32_e32 v70, v20
	v_sub_f32_e32 v20, v89, v217
	v_exp_f32_e32 v71, v20
	v_sub_f32_e32 v20, v90, v217
	v_exp_f32_e32 v184, v20
	v_sub_f32_e32 v20, v91, v217
	v_exp_f32_e32 v185, v20
	v_sub_f32_e32 v20, v92, v217
	v_exp_f32_e32 v188, v20
	v_sub_f32_e32 v20, v93, v217
	v_exp_f32_e32 v189, v20
	v_sub_f32_e32 v20, v94, v217
	v_exp_f32_e32 v202, v20
	v_sub_f32_e32 v20, v95, v217
	v_exp_f32_e32 v203, v20
	v_sub_f32_e32 v20, v96, v217
	v_exp_f32_e32 v204, v20
	v_sub_f32_e32 v20, v97, v217
	v_exp_f32_e32 v205, v20
	v_sub_f32_e32 v20, v98, v217
	v_exp_f32_e32 v206, v20
	v_sub_f32_e32 v20, v99, v217
	v_exp_f32_e32 v207, v20
	v_sub_f32_e32 v20, v100, v217
	v_exp_f32_e32 v74, v20
	v_sub_f32_e32 v20, v101, v217
	v_exp_f32_e32 v75, v20
	v_sub_f32_e32 v20, v102, v217
	v_exp_f32_e32 v92, v20
	v_sub_f32_e32 v20, v103, v217
	v_exp_f32_e32 v93, v20
	v_sub_f32_e32 v20, v104, v217
	v_exp_f32_e32 v94, v20
	v_sub_f32_e32 v20, v105, v217
	v_exp_f32_e32 v95, v20
	v_sub_f32_e32 v20, v106, v217
	v_exp_f32_e32 v96, v20
	v_sub_f32_e32 v20, v107, v217
	v_exp_f32_e32 v97, v20
	v_sub_f32_e32 v20, v108, v217
	v_exp_f32_e32 v98, v20
	v_sub_f32_e32 v20, v109, v217
	v_exp_f32_e32 v99, v20
	v_sub_f32_e32 v20, v110, v217
	v_exp_f32_e32 v100, v20
	v_sub_f32_e32 v20, v111, v217
	v_exp_f32_e32 v101, v20
	v_sub_f32_e32 v20, v112, v217
	v_exp_f32_e32 v102, v20
	v_sub_f32_e32 v20, v113, v217
	v_exp_f32_e32 v103, v20
	v_sub_f32_e32 v20, v114, v217
	v_exp_f32_e32 v104, v20
	v_sub_f32_e32 v20, v115, v217
	v_exp_f32_e32 v105, v20
	v_sub_f32_e32 v20, v116, v217
	v_exp_f32_e32 v76, v20
	v_sub_f32_e32 v20, v117, v217
	v_exp_f32_e32 v77, v20
	v_sub_f32_e32 v20, v118, v217
	v_exp_f32_e32 v80, v20
	v_sub_f32_e32 v20, v119, v217
	v_exp_f32_e32 v81, v20
	v_sub_f32_e32 v20, v120, v217
	v_exp_f32_e32 v84, v20
	v_sub_f32_e32 v20, v121, v217
	v_exp_f32_e32 v85, v20
	v_sub_f32_e32 v20, v122, v217
	v_exp_f32_e32 v88, v20
	v_sub_f32_e32 v20, v123, v217
	v_exp_f32_e32 v89, v20
	v_sub_f32_e32 v20, v124, v217
	v_exp_f32_e32 v78, v20
	v_sub_f32_e32 v20, v125, v217
	v_exp_f32_e32 v79, v20
	v_sub_f32_e32 v20, v126, v217
	v_sub_f32_e32 v4, v4, v217
	v_exp_f32_e32 v82, v20
	v_sub_f32_e32 v20, v127, v217
	v_sub_f32_e32 v5, v5, v217
	v_exp_f32_e32 v4, v4
	v_exp_f32_e32 v83, v20
	v_sub_f32_e32 v20, v128, v217
	v_exp_f32_e32 v5, v5
	v_sub_f32_e32 v6, v6, v217
	v_exp_f32_e32 v86, v20
	v_sub_f32_e32 v20, v129, v217
	v_exp_f32_e32 v6, v6
	v_sub_f32_e32 v7, v7, v217
	v_exp_f32_e32 v87, v20
	v_sub_f32_e32 v20, v130, v217
	v_exp_f32_e32 v7, v7
	v_sub_f32_e32 v8, v8, v217
	v_exp_f32_e32 v90, v20
	v_sub_f32_e32 v20, v131, v217
	v_exp_f32_e32 v8, v8
	v_sub_f32_e32 v9, v9, v217
	v_exp_f32_e32 v91, v20
	v_add_f32_e32 v20, 0, v4
	v_exp_f32_e32 v9, v9
	v_add_f32_e32 v20, v5, v20
	v_add_f32_e32 v20, v6, v20
	v_add_f32_e32 v20, v7, v20
	v_add_f32_e32 v20, v8, v20
	v_add_f32_e32 v20, v9, v20
	v_add_f32_e32 v20, v164, v20
	v_add_f32_e32 v20, v165, v20
	v_add_f32_e32 v20, v166, v20
	v_add_f32_e32 v20, v167, v20
	v_add_f32_e32 v20, v168, v20
	v_add_f32_e32 v20, v169, v20
	v_exp_f32_e32 v10, v10
	v_sub_f32_e32 v11, v21, v217
	v_add_f32_e32 v20, v170, v20
	v_exp_f32_e32 v11, v11
	v_sub_f32_e32 v12, v22, v217
	v_add_f32_e32 v20, v171, v20
	v_exp_f32_e32 v12, v12
	v_sub_f32_e32 v13, v23, v217
	v_add_f32_e32 v20, v172, v20
	v_exp_f32_e32 v13, v13
	v_sub_f32_e32 v14, v24, v217
	v_add_f32_e32 v20, v173, v20
	v_exp_f32_e32 v14, v14
	v_sub_f32_e32 v15, v25, v217
	v_add_f32_e32 v20, v10, v20
	v_exp_f32_e32 v15, v15
	v_add_f32_e32 v20, v11, v20
	v_add_f32_e32 v20, v12, v20
	v_add_f32_e32 v20, v13, v20
	v_add_f32_e32 v20, v14, v20
	v_add_f32_e32 v20, v15, v20
	v_add_f32_e32 v20, v18, v20
	v_add_f32_e32 v20, v19, v20
	v_add_f32_e32 v20, v28, v20
	v_add_f32_e32 v20, v29, v20
	v_add_f32_e32 v20, v30, v20
	v_add_f32_e32 v20, v31, v20
	v_exp_f32_e32 v16, v16
	v_add_f32_e32 v20, v32, v20
	v_exp_f32_e32 v17, v17
	v_add_f32_e32 v20, v33, v20
	v_add_f32_e32 v20, v34, v20
	v_add_f32_e32 v20, v35, v20
	v_add_f32_e32 v20, v16, v20
	v_add_f32_e32 v20, v17, v20
	v_add_f32_e32 v20, v36, v20
	v_add_f32_e32 v20, v37, v20
	v_add_f32_e32 v20, v38, v20
	v_add_f32_e32 v20, v39, v20
	v_add_f32_e32 v20, v40, v20
	v_add_f32_e32 v20, v41, v20
	v_add_f32_e32 v20, v42, v20
	v_add_f32_e32 v20, v43, v20
	v_add_f32_e32 v20, v174, v20
	v_add_f32_e32 v20, v175, v20
	v_add_f32_e32 v20, v176, v20
	v_add_f32_e32 v20, v177, v20
	v_add_f32_e32 v20, v178, v20
	v_add_f32_e32 v20, v179, v20
	v_add_f32_e32 v20, v44, v20
	v_add_f32_e32 v20, v45, v20
	v_add_f32_e32 v20, v46, v20
	v_add_f32_e32 v20, v47, v20
	v_add_f32_e32 v20, v48, v20
	v_add_f32_e32 v20, v49, v20
	v_add_f32_e32 v20, v50, v20
	v_add_f32_e32 v20, v51, v20
	v_add_f32_e32 v20, v56, v20
	v_add_f32_e32 v20, v57, v20
	v_add_f32_e32 v20, v60, v20
	v_add_f32_e32 v20, v61, v20
	v_add_f32_e32 v20, v180, v20
	v_add_f32_e32 v20, v181, v20
	v_add_f32_e32 v20, v182, v20
	v_add_f32_e32 v20, v183, v20
	v_add_f32_e32 v20, v52, v20
	v_add_f32_e32 v20, v53, v20
	v_add_f32_e32 v20, v54, v20
	v_add_f32_e32 v20, v55, v20
	v_add_f32_e32 v20, v58, v20
	v_add_f32_e32 v20, v59, v20
	v_add_f32_e32 v20, v64, v20
	v_add_f32_e32 v20, v65, v20
	v_add_f32_e32 v20, v68, v20
	v_add_f32_e32 v20, v69, v20
	v_add_f32_e32 v20, v72, v20
	v_add_f32_e32 v20, v73, v20
	v_add_f32_e32 v20, v186, v20
	v_add_f32_e32 v20, v187, v20
	v_add_f32_e32 v20, v190, v20
	v_add_f32_e32 v20, v191, v20
	v_add_f32_e32 v20, v62, v20
	v_add_f32_e32 v20, v63, v20
	v_add_f32_e32 v20, v66, v20
	v_add_f32_e32 v20, v67, v20
	v_add_f32_e32 v20, v70, v20
	v_add_f32_e32 v20, v71, v20
	v_add_f32_e32 v20, v184, v20
	v_add_f32_e32 v20, v185, v20
	v_add_f32_e32 v20, v188, v20
	v_add_f32_e32 v20, v189, v20
	v_add_f32_e32 v20, v202, v20
	v_add_f32_e32 v20, v203, v20
	v_add_f32_e32 v20, v204, v20
	v_add_f32_e32 v20, v205, v20
	v_add_f32_e32 v20, v206, v20
	v_add_f32_e32 v20, v207, v20
	v_add_f32_e32 v20, v74, v20
	v_add_f32_e32 v20, v75, v20
	v_add_f32_e32 v20, v92, v20
	v_add_f32_e32 v20, v93, v20
	v_add_f32_e32 v20, v94, v20
	v_add_f32_e32 v20, v95, v20
	v_add_f32_e32 v20, v96, v20
	v_add_f32_e32 v20, v97, v20
	v_add_f32_e32 v20, v98, v20
	v_add_f32_e32 v20, v99, v20
	v_add_f32_e32 v20, v100, v20
	v_add_f32_e32 v20, v101, v20
	v_add_f32_e32 v20, v102, v20
	v_add_f32_e32 v20, v103, v20
	v_add_f32_e32 v20, v104, v20
	v_add_f32_e32 v20, v105, v20
	v_add_f32_e32 v20, v76, v20
	v_add_f32_e32 v20, v77, v20
	v_add_f32_e32 v20, v80, v20
	v_add_f32_e32 v20, v81, v20
	v_add_f32_e32 v20, v84, v20
	v_add_f32_e32 v20, v85, v20
	v_add_f32_e32 v20, v88, v20
	v_add_f32_e32 v20, v89, v20
	v_add_f32_e32 v20, v78, v20
	v_add_f32_e32 v20, v79, v20
	v_add_f32_e32 v20, v82, v20
	v_add_f32_e32 v20, v83, v20
	v_add_f32_e32 v20, v86, v20
	v_add_f32_e32 v20, v87, v20
	v_add_f32_e32 v20, v90, v20
	v_add_f32_e32 v20, v91, v20
	ds_bpermute_b32 v21, v216, v20
	s_waitcnt lgkmcnt(0)
	v_add_f32_e32 v20, v20, v21
	v_div_scale_f32 v21, s[42:43], v20, v20, 1.0
	v_rcp_f32_e32 v22, v21
	s_nop 0
	v_fma_f32 v23, -v21, v22, 1.0
	v_fmac_f32_e32 v22, v23, v22
	v_div_scale_f32 v23, vcc, 1.0, v20, 1.0
	v_mul_f32_e32 v24, v23, v22
	v_fma_f32 v25, -v21, v24, v23
	v_fmac_f32_e32 v24, v25, v22
	v_fma_f32 v21, -v21, v24, v23
	v_div_fmas_f32 v21, v21, v22, v24
	v_div_fixup_f32 v106, v21, v20, 1.0
	v_pk_mul_f32 v[6:7], v[6:7], v[106:107] op_sel_hi:[1,0]
	v_pk_mul_f32 v[4:5], v[4:5], v[106:107] op_sel_hi:[1,0]
	v_pk_mul_f32 v[8:9], v[8:9], v[106:107] op_sel_hi:[1,0]
	v_cvt_pk_bf16_f32 v21, v6, v7
	v_pk_mul_f32 v[6:7], v[12:13], v[106:107] op_sel_hi:[1,0]
	v_pk_mul_f32 v[24:25], v[164:165], v[106:107] op_sel_hi:[1,0]
	v_pk_mul_f32 v[108:109], v[168:169], v[106:107] op_sel_hi:[1,0]
	v_cvt_pk_bf16_f32 v20, v4, v5
	v_cvt_pk_bf16_f32 v22, v8, v9
	v_pk_mul_f32 v[4:5], v[10:11], v[106:107] op_sel_hi:[1,0]
	v_pk_mul_f32 v[8:9], v[14:15], v[106:107] op_sel_hi:[1,0]
	v_pk_mul_f32 v[10:11], v[18:19], v[106:107] op_sel_hi:[1,0]
	v_pk_mul_f32 v[18:19], v[32:33], v[106:107] op_sel_hi:[1,0]
	v_cvt_pk_bf16_f32 v33, v6, v7
	v_pk_mul_f32 v[6:7], v[36:37], v[106:107] op_sel_hi:[1,0]
	v_cvt_pk_bf16_f32 v23, v24, v25
	v_cvt_pk_bf16_f32 v25, v108, v109
	v_pk_mul_f32 v[108:109], v[34:35], v[106:107] op_sel_hi:[1,0]
	v_cvt_pk_bf16_f32 v32, v4, v5
	v_cvt_pk_bf16_f32 v34, v8, v9
	v_pk_mul_f32 v[4:5], v[16:17], v[106:107] op_sel_hi:[1,0]
	v_pk_mul_f32 v[8:9], v[38:39], v[106:107] op_sel_hi:[1,0]
	v_cvt_pk_bf16_f32 v37, v6, v7
	v_pk_mul_f32 v[6:7], v[46:47], v[106:107] op_sel_hi:[1,0]
	v_cvt_pk_bf16_f32 v35, v10, v11
	v_pk_mul_f32 v[10:11], v[40:41], v[106:107] op_sel_hi:[1,0]
	v_cvt_pk_bf16_f32 v36, v4, v5
	v_cvt_pk_bf16_f32 v38, v8, v9
	v_pk_mul_f32 v[4:5], v[44:45], v[106:107] op_sel_hi:[1,0]
	v_pk_mul_f32 v[8:9], v[48:49], v[106:107] op_sel_hi:[1,0]
	v_cvt_pk_bf16_f32 v49, v6, v7
	v_pk_mul_f32 v[6:7], v[54:55], v[106:107] op_sel_hi:[1,0]
	v_pk_mul_f32 v[12:13], v[28:29], v[106:107] op_sel_hi:[1,0]
	v_cvt_pk_bf16_f32 v39, v10, v11
	v_pk_mul_f32 v[10:11], v[50:51], v[106:107] op_sel_hi:[1,0]
	v_cvt_pk_bf16_f32 v48, v4, v5
	v_pk_mul_f32 v[4:5], v[52:53], v[106:107] op_sel_hi:[1,0]
	v_cvt_pk_bf16_f32 v53, v6, v7
	v_pk_mul_f32 v[6:7], v[66:67], v[106:107] op_sel_hi:[1,0]
	v_cvt_pk_bf16_f32 v28, v12, v13
	v_pk_mul_f32 v[12:13], v[42:43], v[106:107] op_sel_hi:[1,0]
	v_cvt_pk_bf16_f32 v51, v10, v11
	v_pk_mul_f32 v[10:11], v[64:65], v[106:107] op_sel_hi:[1,0]
	v_cvt_pk_bf16_f32 v52, v4, v5
	v_pk_mul_f32 v[4:5], v[62:63], v[106:107] op_sel_hi:[1,0]
	v_cvt_pk_bf16_f32 v65, v6, v7
	v_pk_mul_f32 v[6:7], v[92:93], v[106:107] op_sel_hi:[1,0]
	v_add_u32_e32 v92, s11, v215
	v_pk_mul_f32 v[14:15], v[30:31], v[106:107] op_sel_hi:[1,0]
	v_cvt_pk_bf16_f32 v40, v12, v13
	v_pk_mul_f32 v[12:13], v[56:57], v[106:107] op_sel_hi:[1,0]
	v_cvt_pk_bf16_f32 v64, v4, v5
	v_pk_mul_f32 v[4:5], v[74:75], v[106:107] op_sel_hi:[1,0]
	v_mad_u32_u24 v93, v213, s8, v92
	v_cvt_pk_bf16_f32 v29, v14, v15
	v_cvt_pk_bf16_f32 v30, v18, v19
	v_pk_mul_f32 v[14:15], v[174:175], v[106:107] op_sel_hi:[1,0]
	v_pk_mul_f32 v[16:17], v[176:177], v[106:107] op_sel_hi:[1,0]
	v_pk_mul_f32 v[18:19], v[178:179], v[106:107] op_sel_hi:[1,0]
	v_cvt_pk_bf16_f32 v44, v12, v13
	v_pk_mul_f32 v[12:13], v[68:69], v[106:107] op_sel_hi:[1,0]
	v_cvt_pk_bf16_f32 v68, v4, v5
	v_cvt_pk_bf16_f32 v69, v6, v7
	ds_read2_b64 v[4:7], v93 offset1:2
	v_cvt_pk_bf16_f32 v41, v14, v15
	v_cvt_pk_bf16_f32 v42, v16, v17
	v_cvt_pk_bf16_f32 v43, v18, v19
	v_pk_mul_f32 v[14:15], v[60:61], v[106:107] op_sel_hi:[1,0]
	v_pk_mul_f32 v[16:17], v[180:181], v[106:107] op_sel_hi:[1,0]
	v_pk_mul_f32 v[18:19], v[182:183], v[106:107] op_sel_hi:[1,0]
	v_cvt_pk_bf16_f32 v50, v8, v9
	v_cvt_pk_bf16_f32 v45, v14, v15
	v_cvt_pk_bf16_f32 v46, v16, v17
	v_cvt_pk_bf16_f32 v47, v18, v19
	v_pk_mul_f32 v[8:9], v[58:59], v[106:107] op_sel_hi:[1,0]
	v_pk_mul_f32 v[14:15], v[72:73], v[106:107] op_sel_hi:[1,0]
	v_pk_mul_f32 v[16:17], v[186:187], v[106:107] op_sel_hi:[1,0]
	v_pk_mul_f32 v[18:19], v[190:191], v[106:107] op_sel_hi:[1,0]
	v_cvt_pk_bf16_f32 v54, v8, v9
	v_cvt_pk_bf16_f32 v55, v10, v11
	v_cvt_pk_bf16_f32 v56, v12, v13
	v_cvt_pk_bf16_f32 v57, v14, v15
	v_cvt_pk_bf16_f32 v58, v16, v17
	v_cvt_pk_bf16_f32 v59, v18, v19
	v_pk_mul_f32 v[8:9], v[70:71], v[106:107] op_sel_hi:[1,0]
	v_pk_mul_f32 v[10:11], v[184:185], v[106:107] op_sel_hi:[1,0]
	v_pk_mul_f32 v[12:13], v[188:189], v[106:107] op_sel_hi:[1,0]
	v_pk_mul_f32 v[14:15], v[202:203], v[106:107] op_sel_hi:[1,0]
	v_pk_mul_f32 v[16:17], v[204:205], v[106:107] op_sel_hi:[1,0]
	v_pk_mul_f32 v[18:19], v[206:207], v[106:107] op_sel_hi:[1,0]
	v_cvt_pk_bf16_f32 v66, v8, v9
	v_cvt_pk_bf16_f32 v67, v10, v11
	v_cvt_pk_bf16_f32 v60, v12, v13
	v_cvt_pk_bf16_f32 v61, v14, v15
	v_cvt_pk_bf16_f32 v62, v16, v17
	v_cvt_pk_bf16_f32 v63, v18, v19
	v_pk_mul_f32 v[8:9], v[94:95], v[106:107] op_sel_hi:[1,0]
	v_pk_mul_f32 v[10:11], v[96:97], v[106:107] op_sel_hi:[1,0]
	v_pk_mul_f32 v[12:13], v[98:99], v[106:107] op_sel_hi:[1,0]
	v_pk_mul_f32 v[14:15], v[100:101], v[106:107] op_sel_hi:[1,0]
	v_pk_mul_f32 v[16:17], v[102:103], v[106:107] op_sel_hi:[1,0]
	v_pk_mul_f32 v[18:19], v[104:105], v[106:107] op_sel_hi:[1,0]
	v_cvt_pk_bf16_f32 v70, v8, v9
	v_cvt_pk_bf16_f32 v71, v10, v11
	v_cvt_pk_bf16_f32 v72, v12, v13
	v_cvt_pk_bf16_f32 v73, v14, v15
	v_cvt_pk_bf16_f32 v74, v16, v17
	v_cvt_pk_bf16_f32 v75, v18, v19
	s_waitcnt lgkmcnt(0)
	v_mfma_f32_32x32x16_bf16 v[4:19], v[20:23], v[4:7], 0
	v_mul_f32_e64 v26, v166, v106
	v_mul_f32_e64 v27, v167, v106
	v_mul_f32_e64 v110, v170, v106
	v_mul_f32_e64 v111, v171, v106
	v_mul_f32_e64 v112, v172, v106
	v_mul_f32_e64 v113, v173, v106
	v_cvt_pk_bf16_f32 v24, v26, v27
	v_cvt_pk_bf16_f32 v26, v110, v111
	v_cvt_pk_bf16_f32 v27, v112, v113
	v_pk_mul_f32 v[94:95], v[80:81], v[106:107] op_sel_hi:[1,0]
	v_pk_mul_f32 v[96:97], v[78:79], v[106:107] op_sel_hi:[1,0]
	ds_read2_b64 v[78:81], v93 offset0:4 offset1:6
	s_waitcnt lgkmcnt(0)
	v_mfma_f32_32x32x16_bf16 v[4:19], v[24:27], v[78:81], v[4:19]
	v_mul_f32_e64 v84, v84, v106
	v_mul_f32_e64 v85, v85, v106
	v_mul_f32_e64 v98, v86, v106
	v_mul_f32_e64 v99, v87, v106
	v_cvt_pk_bf16_f32 v78, v84, v85
	ds_read2_b64 v[84:87], v93 offset0:8 offset1:10
	v_pk_mul_f32 v[88:89], v[88:89], v[106:107] op_sel_hi:[1,0]
	v_cvt_pk_bf16_f32 v31, v108, v109
	v_cvt_pk_bf16_f32 v79, v88, v89
	s_waitcnt lgkmcnt(0)
	v_mfma_f32_32x32x16_bf16 v[4:19], v[32:35], v[84:87], v[4:19]
	ds_read2_b64 v[86:89], v93 offset0:12 offset1:14
	v_lshrrev_b32_e32 v84, 3, v211
	v_and_b32_e32 v84, 4, v84
	v_lshlrev_b32_e32 v85, 1, v211
	v_mul_f32_e64 v76, v76, v106
	v_mul_f32_e64 v77, v77, v106
	v_pk_mul_f32 v[82:83], v[82:83], v[106:107] op_sel_hi:[1,0]
	v_pk_mul_f32 v[90:91], v[90:91], v[106:107] op_sel_hi:[1,0]
	v_mul_u32_u24_e32 v84, 0x110, v84
	v_and_b32_e32 v85, 62, v85
	v_cvt_pk_bf16_f32 v76, v76, v77
	v_cvt_pk_bf16_f32 v77, v94, v95
	v_cvt_pk_bf16_f32 v80, v96, v97
	v_cvt_pk_bf16_f32 v81, v82, v83
	v_cvt_pk_bf16_f32 v82, v98, v99
	v_cvt_pk_bf16_f32 v83, v90, v91
	v_add3_u32 v84, s4, v84, v85
	s_waitcnt lgkmcnt(0)
	v_mfma_f32_32x32x16_bf16 v[4:19], v[28:31], v[86:89], v[4:19]
	ds_read2_b64 v[86:89], v93 offset0:16 offset1:18
	s_waitcnt lgkmcnt(0)
	v_mfma_f32_32x32x16_bf16 v[4:19], v[36:39], v[86:89], v[4:19]
	ds_read2_b64 v[86:89], v93 offset0:20 offset1:22
	s_waitcnt lgkmcnt(0)
	v_mfma_f32_32x32x16_bf16 v[4:19], v[40:43], v[86:89], v[4:19]
	ds_read2_b64 v[86:89], v93 offset0:24 offset1:26
	s_waitcnt lgkmcnt(0)
	v_mfma_f32_32x32x16_bf16 v[4:19], v[48:51], v[86:89], v[4:19]
	ds_read2_b64 v[86:89], v93 offset0:28 offset1:30
	s_waitcnt lgkmcnt(0)
	v_mfma_f32_32x32x16_bf16 v[4:19], v[44:47], v[86:89], v[4:19]
	ds_read2_b64 v[86:89], v93 offset0:32 offset1:34
	s_waitcnt lgkmcnt(0)
	v_mfma_f32_32x32x16_bf16 v[4:19], v[52:55], v[86:89], v[4:19]
	ds_read2_b64 v[86:89], v93 offset0:36 offset1:38
	s_waitcnt lgkmcnt(0)
	v_mfma_f32_32x32x16_bf16 v[4:19], v[56:59], v[86:89], v[4:19]
	ds_read2_b64 v[86:89], v93 offset0:40 offset1:42
	s_waitcnt lgkmcnt(0)
	v_mfma_f32_32x32x16_bf16 v[4:19], v[64:67], v[86:89], v[4:19]
	ds_read2_b64 v[86:89], v93 offset0:44 offset1:46
	s_waitcnt lgkmcnt(0)
	v_mfma_f32_32x32x16_bf16 v[4:19], v[60:63], v[86:89], v[4:19]
	ds_read2_b64 v[86:89], v93 offset0:48 offset1:50
	s_waitcnt lgkmcnt(0)
	v_mfma_f32_32x32x16_bf16 v[4:19], v[68:71], v[86:89], v[4:19]
	ds_read2_b64 v[86:89], v93 offset0:52 offset1:54
	s_waitcnt lgkmcnt(0)
	v_mfma_f32_32x32x16_bf16 v[4:19], v[72:75], v[86:89], v[4:19]
	ds_read2_b64 v[86:89], v93 offset0:56 offset1:58
	s_waitcnt lgkmcnt(0)
	v_mfma_f32_32x32x16_bf16 v[4:19], v[76:79], v[86:89], v[4:19]
	ds_read2_b64 v[86:89], v93 offset0:60 offset1:62
	s_waitcnt lgkmcnt(0)
	v_mfma_f32_32x32x16_bf16 v[4:19], v[80:83], v[86:89], v[4:19]
	s_nop 11
	v_cvt_pk_bf16_f32 v4, v4, v5
	ds_write_b16 v84, v4
	ds_write_b16_d16_hi v84, v4 offset:272
	v_cvt_pk_bf16_f32 v4, v6, v7
	ds_write_b16 v84, v4 offset:544
	ds_write_b16_d16_hi v84, v4 offset:816
	v_cvt_pk_bf16_f32 v4, v8, v9
	ds_write_b16 v84, v4 offset:2176
	ds_write_b16_d16_hi v84, v4 offset:2448
	v_cvt_pk_bf16_f32 v4, v10, v11
	ds_write_b16 v84, v4 offset:2720
	ds_write_b16_d16_hi v84, v4 offset:2992
	v_cvt_pk_bf16_f32 v4, v12, v13
	ds_write_b16 v84, v4 offset:4352
	ds_write_b16_d16_hi v84, v4 offset:4624
	v_cvt_pk_bf16_f32 v4, v14, v15
	ds_write_b16 v84, v4 offset:4896
	ds_write_b16_d16_hi v84, v4 offset:5168
	v_cvt_pk_bf16_f32 v4, v16, v17
	ds_write_b16 v84, v4 offset:6528
	ds_write_b16_d16_hi v84, v4 offset:6800
	v_cvt_pk_bf16_f32 v4, v18, v19
	ds_write_b16 v84, v4 offset:7072
	ds_write_b16_d16_hi v84, v4 offset:7344
	v_add_u32_e32 v85, 0x4000, v93
	ds_read2_b64 v[4:7], v85 offset0:32 offset1:34
	ds_read2_b64 v[86:89], v85 offset0:36 offset1:38
	ds_read2_b64 v[94:97], v85 offset0:40 offset1:42
	ds_read2_b64 v[98:101], v85 offset0:44 offset1:46
	ds_read2_b64 v[102:105], v85 offset0:48 offset1:50
	s_waitcnt lgkmcnt(4)
	v_mfma_f32_32x32x16_bf16 v[4:19], v[20:23], v[4:7], 0
	s_waitcnt lgkmcnt(3)
	v_mfma_f32_32x32x16_bf16 v[4:19], v[24:27], v[86:89], v[4:19]
	ds_read2_b64 v[86:89], v85 offset0:52 offset1:54
	s_waitcnt lgkmcnt(3)
	v_mfma_f32_32x32x16_bf16 v[4:19], v[32:35], v[94:97], v[4:19]
	ds_read2_b64 v[94:97], v85 offset0:56 offset1:58
	s_waitcnt lgkmcnt(3)
	v_mfma_f32_32x32x16_bf16 v[4:19], v[28:31], v[98:101], v[4:19]
	ds_read2_b64 v[98:101], v85 offset0:60 offset1:62
	s_waitcnt lgkmcnt(3)
	v_mfma_f32_32x32x16_bf16 v[4:19], v[36:39], v[102:105], v[4:19]
	ds_read2_b64 v[102:105], v85 offset0:64 offset1:66
	s_waitcnt lgkmcnt(3)
	v_mfma_f32_32x32x16_bf16 v[4:19], v[40:43], v[86:89], v[4:19]
	ds_read2_b64 v[86:89], v85 offset0:68 offset1:70
	s_waitcnt lgkmcnt(3)
	v_mfma_f32_32x32x16_bf16 v[4:19], v[48:51], v[94:97], v[4:19]
	ds_read2_b64 v[94:97], v85 offset0:72 offset1:74
	s_waitcnt lgkmcnt(3)
	v_mfma_f32_32x32x16_bf16 v[4:19], v[44:47], v[98:101], v[4:19]
	ds_read2_b64 v[98:101], v85 offset0:76 offset1:78
	s_waitcnt lgkmcnt(3)
	v_mfma_f32_32x32x16_bf16 v[4:19], v[52:55], v[102:105], v[4:19]
	ds_read2_b64 v[102:105], v85 offset0:80 offset1:82
	s_waitcnt lgkmcnt(3)
	v_mfma_f32_32x32x16_bf16 v[4:19], v[56:59], v[86:89], v[4:19]
	ds_read2_b64 v[86:89], v85 offset0:84 offset1:86
	s_waitcnt lgkmcnt(3)
	v_mfma_f32_32x32x16_bf16 v[4:19], v[64:67], v[94:97], v[4:19]
	ds_read2_b64 v[94:97], v85 offset0:88 offset1:90
	s_waitcnt lgkmcnt(3)
	v_mfma_f32_32x32x16_bf16 v[4:19], v[60:63], v[98:101], v[4:19]
	ds_read2_b64 v[98:101], v85 offset0:92 offset1:94
	s_waitcnt lgkmcnt(3)
	v_mfma_f32_32x32x16_bf16 v[4:19], v[68:71], v[102:105], v[4:19]
	s_waitcnt lgkmcnt(2)
	v_mfma_f32_32x32x16_bf16 v[4:19], v[72:75], v[86:89], v[4:19]
	s_waitcnt lgkmcnt(1)
	v_mfma_f32_32x32x16_bf16 v[4:19], v[76:79], v[94:97], v[4:19]
	s_waitcnt lgkmcnt(0)
	v_mfma_f32_32x32x16_bf16 v[4:19], v[80:83], v[98:101], v[4:19]
	s_nop 11
	v_cvt_pk_bf16_f32 v4, v4, v5
	ds_write_b16 v84, v4 offset:64
	ds_write_b16_d16_hi v84, v4 offset:336
	v_cvt_pk_bf16_f32 v4, v6, v7
	ds_write_b16 v84, v4 offset:608
	ds_write_b16_d16_hi v84, v4 offset:880
	v_cvt_pk_bf16_f32 v4, v8, v9
	ds_write_b16 v84, v4 offset:2240
	ds_write_b16_d16_hi v84, v4 offset:2512
	v_cvt_pk_bf16_f32 v4, v10, v11
	ds_write_b16 v84, v4 offset:2784
	ds_write_b16_d16_hi v84, v4 offset:3056
	v_cvt_pk_bf16_f32 v4, v12, v13
	ds_write_b16 v84, v4 offset:4416
	ds_write_b16_d16_hi v84, v4 offset:4688
	v_cvt_pk_bf16_f32 v4, v14, v15
	ds_write_b16 v84, v4 offset:4960
	ds_write_b16_d16_hi v84, v4 offset:5232
	v_cvt_pk_bf16_f32 v4, v16, v17
	ds_write_b16 v84, v4 offset:6592
	ds_write_b16_d16_hi v84, v4 offset:6864
	v_cvt_pk_bf16_f32 v4, v18, v19
	ds_write_b16 v84, v4 offset:7136
	ds_write_b16_d16_hi v84, v4 offset:7408
	v_mad_u32_u24 v85, v214, s8, v92
	ds_read2_b64 v[4:7], v85 offset1:2
	ds_read2_b64 v[86:89], v85 offset0:4 offset1:6
	ds_read2_b64 v[94:97], v85 offset0:8 offset1:10
	ds_read2_b64 v[98:101], v85 offset0:12 offset1:14
	ds_read2_b64 v[102:105], v85 offset0:16 offset1:18
	s_waitcnt lgkmcnt(4)
	v_mfma_f32_32x32x16_bf16 v[4:19], v[20:23], v[4:7], 0
	s_waitcnt lgkmcnt(3)
	v_mfma_f32_32x32x16_bf16 v[4:19], v[24:27], v[86:89], v[4:19]
	ds_read2_b64 v[86:89], v85 offset0:20 offset1:22
	s_waitcnt lgkmcnt(3)
	v_mfma_f32_32x32x16_bf16 v[4:19], v[32:35], v[94:97], v[4:19]
	ds_read2_b64 v[94:97], v85 offset0:24 offset1:26
	s_waitcnt lgkmcnt(3)
	v_mfma_f32_32x32x16_bf16 v[4:19], v[28:31], v[98:101], v[4:19]
	ds_read2_b64 v[98:101], v85 offset0:28 offset1:30
	s_waitcnt lgkmcnt(3)
	v_mfma_f32_32x32x16_bf16 v[4:19], v[36:39], v[102:105], v[4:19]
	ds_read2_b64 v[102:105], v85 offset0:32 offset1:34
	s_waitcnt lgkmcnt(3)
	v_mfma_f32_32x32x16_bf16 v[4:19], v[40:43], v[86:89], v[4:19]
	ds_read2_b64 v[86:89], v85 offset0:36 offset1:38
	s_waitcnt lgkmcnt(3)
	v_mfma_f32_32x32x16_bf16 v[4:19], v[48:51], v[94:97], v[4:19]
	ds_read2_b64 v[94:97], v85 offset0:40 offset1:42
	s_waitcnt lgkmcnt(3)
	v_mfma_f32_32x32x16_bf16 v[4:19], v[44:47], v[98:101], v[4:19]
	ds_read2_b64 v[98:101], v85 offset0:44 offset1:46
	s_waitcnt lgkmcnt(3)
	v_mfma_f32_32x32x16_bf16 v[4:19], v[52:55], v[102:105], v[4:19]
	ds_read2_b64 v[102:105], v85 offset0:48 offset1:50
	s_waitcnt lgkmcnt(3)
	v_mfma_f32_32x32x16_bf16 v[4:19], v[56:59], v[86:89], v[4:19]
	ds_read2_b64 v[86:89], v85 offset0:52 offset1:54
	s_waitcnt lgkmcnt(3)
	v_mfma_f32_32x32x16_bf16 v[4:19], v[64:67], v[94:97], v[4:19]
	ds_read2_b64 v[94:97], v85 offset0:56 offset1:58
	s_waitcnt lgkmcnt(3)
	v_mfma_f32_32x32x16_bf16 v[4:19], v[60:63], v[98:101], v[4:19]
	ds_read2_b64 v[98:101], v85 offset0:60 offset1:62
	s_waitcnt lgkmcnt(3)
	v_mfma_f32_32x32x16_bf16 v[4:19], v[68:71], v[102:105], v[4:19]
	s_waitcnt lgkmcnt(2)
	v_mfma_f32_32x32x16_bf16 v[4:19], v[72:75], v[86:89], v[4:19]
	s_waitcnt lgkmcnt(1)
	v_mfma_f32_32x32x16_bf16 v[4:19], v[76:79], v[94:97], v[4:19]
	s_waitcnt lgkmcnt(0)
	v_mfma_f32_32x32x16_bf16 v[4:19], v[80:83], v[98:101], v[4:19]
	s_nop 11
	v_cvt_pk_bf16_f32 v4, v4, v5
	ds_write_b16 v84, v4 offset:128
	ds_write_b16_d16_hi v84, v4 offset:400
	v_cvt_pk_bf16_f32 v4, v6, v7
	ds_write_b16 v84, v4 offset:672
	ds_write_b16_d16_hi v84, v4 offset:944
	v_cvt_pk_bf16_f32 v4, v8, v9
	ds_write_b16 v84, v4 offset:2304
	ds_write_b16_d16_hi v84, v4 offset:2576
	v_cvt_pk_bf16_f32 v4, v10, v11
	ds_write_b16 v84, v4 offset:2848
	ds_write_b16_d16_hi v84, v4 offset:3120
	v_cvt_pk_bf16_f32 v4, v12, v13
	ds_write_b16 v84, v4 offset:4480
	ds_write_b16_d16_hi v84, v4 offset:4752
	v_cvt_pk_bf16_f32 v4, v14, v15
	ds_write_b16 v84, v4 offset:5024
	ds_write_b16_d16_hi v84, v4 offset:5296
	v_cvt_pk_bf16_f32 v4, v16, v17
	ds_write_b16 v84, v4 offset:6656
	ds_write_b16_d16_hi v84, v4 offset:6928
	v_cvt_pk_bf16_f32 v4, v18, v19
	ds_write_b16 v84, v4 offset:7200
	ds_write_b16_d16_hi v84, v4 offset:7472
	v_mad_u32_u24 v85, v212, s8, v92
	ds_read2_b64 v[4:7], v85 offset1:2
	ds_read2_b64 v[86:89], v85 offset0:4 offset1:6
	ds_read2_b64 v[94:97], v85 offset0:8 offset1:10
	ds_read2_b64 v[98:101], v85 offset0:12 offset1:14
	ds_read2_b64 v[102:105], v85 offset0:16 offset1:18
	s_waitcnt lgkmcnt(4)
	v_mfma_f32_32x32x16_bf16 v[4:19], v[20:23], v[4:7], 0
	s_waitcnt lgkmcnt(3)
	v_mfma_f32_32x32x16_bf16 v[4:19], v[24:27], v[86:89], v[4:19]
	ds_read2_b64 v[86:89], v85 offset0:20 offset1:22
	s_waitcnt lgkmcnt(3)
	v_mfma_f32_32x32x16_bf16 v[4:19], v[32:35], v[94:97], v[4:19]
	ds_read2_b64 v[94:97], v85 offset0:24 offset1:26
	s_waitcnt lgkmcnt(3)
	v_mfma_f32_32x32x16_bf16 v[4:19], v[28:31], v[98:101], v[4:19]
	ds_read2_b64 v[98:101], v85 offset0:28 offset1:30
	s_waitcnt lgkmcnt(3)
	v_mfma_f32_32x32x16_bf16 v[4:19], v[36:39], v[102:105], v[4:19]
	ds_read2_b64 v[102:105], v85 offset0:32 offset1:34
	s_waitcnt lgkmcnt(3)
	v_mfma_f32_32x32x16_bf16 v[4:19], v[40:43], v[86:89], v[4:19]
	ds_read2_b64 v[86:89], v85 offset0:36 offset1:38
	s_waitcnt lgkmcnt(3)
	v_mfma_f32_32x32x16_bf16 v[4:19], v[48:51], v[94:97], v[4:19]
	ds_read2_b64 v[94:97], v85 offset0:40 offset1:42
	s_waitcnt lgkmcnt(3)
	v_mfma_f32_32x32x16_bf16 v[4:19], v[44:47], v[98:101], v[4:19]
	ds_read2_b64 v[98:101], v85 offset0:44 offset1:46
	s_waitcnt lgkmcnt(3)
	v_mfma_f32_32x32x16_bf16 v[4:19], v[52:55], v[102:105], v[4:19]
	ds_read2_b64 v[102:105], v85 offset0:48 offset1:50
	s_waitcnt lgkmcnt(3)
	v_mfma_f32_32x32x16_bf16 v[4:19], v[56:59], v[86:89], v[4:19]
	ds_read2_b64 v[86:89], v85 offset0:52 offset1:54
	s_waitcnt lgkmcnt(3)
	v_mfma_f32_32x32x16_bf16 v[4:19], v[64:67], v[94:97], v[4:19]
	ds_read2_b64 v[94:97], v85 offset0:56 offset1:58
	s_waitcnt lgkmcnt(3)
	v_mfma_f32_32x32x16_bf16 v[4:19], v[60:63], v[98:101], v[4:19]
	ds_read2_b64 v[98:101], v85 offset0:60 offset1:62
	s_waitcnt lgkmcnt(3)
	v_mfma_f32_32x32x16_bf16 v[4:19], v[68:71], v[102:105], v[4:19]
	s_waitcnt lgkmcnt(2)
	v_mfma_f32_32x32x16_bf16 v[4:19], v[72:75], v[86:89], v[4:19]
	s_waitcnt lgkmcnt(1)
	v_mfma_f32_32x32x16_bf16 v[4:19], v[76:79], v[94:97], v[4:19]
	s_waitcnt lgkmcnt(0)
	v_mfma_f32_32x32x16_bf16 v[4:19], v[80:83], v[98:101], v[4:19]
	s_nop 11
	v_cvt_pk_bf16_f32 v4, v4, v5
	ds_write_b16 v84, v4 offset:192
	ds_write_b16_d16_hi v84, v4 offset:464
	v_cvt_pk_bf16_f32 v4, v6, v7
	ds_write_b16 v84, v4 offset:736
	ds_write_b16_d16_hi v84, v4 offset:1008
	v_cvt_pk_bf16_f32 v4, v8, v9
	ds_write_b16 v84, v4 offset:2368
	ds_write_b16_d16_hi v84, v4 offset:2640
	v_cvt_pk_bf16_f32 v4, v10, v11
	ds_write_b16 v84, v4 offset:2912
	ds_write_b16_d16_hi v84, v4 offset:3184
	v_cvt_pk_bf16_f32 v4, v12, v13
	ds_write_b16 v84, v4 offset:4544
	ds_write_b16_d16_hi v84, v4 offset:4816
	v_cvt_pk_bf16_f32 v4, v14, v15
	ds_write_b16 v84, v4 offset:5088
	ds_write_b16_d16_hi v84, v4 offset:5360
	v_cvt_pk_bf16_f32 v4, v16, v17
	ds_write_b16 v84, v4 offset:6720
	ds_write_b16_d16_hi v84, v4 offset:6992
	v_cvt_pk_bf16_f32 v4, v18, v19
	ds_write_b16 v84, v4 offset:7264
	ds_write_b16_d16_hi v84, v4 offset:7536
	v_mul_u32_u24_e32 v4, 0x110, v201
	v_add3_u32 v6, s4, v4, v2
	ds_read_b128 v[8:11], v6
	s_mulk_i32 s39, 0xc00
	s_mul_hi_u32 s41, s38, 0xc00
	s_waitcnt vmcnt(7)
	v_lshlrev_b32_e32 v14, 16, v160
	v_and_b32_e32 v15, 0xffff0000, v160
	s_waitcnt lgkmcnt(0)
	v_lshlrev_b32_e32 v12, 16, v8
	v_and_b32_e32 v13, 0xffff0000, v8
	s_add_i32 s41, s41, s39
	s_mulk_i32 s38, 0xc00
	v_pk_mul_f32 v[12:13], v[14:15], v[12:13]
	s_add_u32 s38, s36, s38
	v_cvt_pk_bf16_f32 v8, v12, v13
	v_lshlrev_b32_e32 v12, 16, v9
	v_and_b32_e32 v13, 0xffff0000, v9
	v_lshlrev_b32_e32 v14, 16, v161
	v_and_b32_e32 v15, 0xffff0000, v161
	s_addc_u32 s39, s37, s41
	v_pk_mul_f32 v[12:13], v[14:15], v[12:13]
	s_add_u32 s38, s38, s24
	v_mul_u32_u24_e32 v4, 0x600, v201
	v_cvt_pk_bf16_f32 v9, v12, v13
	v_lshlrev_b32_e32 v12, 16, v10
	v_and_b32_e32 v13, 0xffff0000, v10
	v_lshlrev_b32_e32 v14, 16, v162
	v_and_b32_e32 v15, 0xffff0000, v162
	s_addc_u32 s39, s39, 0
	v_lshlrev_b32_e32 v4, 1, v4
	v_mov_b32_e32 v5, v3
	v_pk_mul_f32 v[12:13], v[14:15], v[12:13]
	v_lshl_add_u64 v[4:5], s[38:39], 0, v[4:5]
	v_cvt_pk_bf16_f32 v10, v12, v13
	v_lshlrev_b32_e32 v12, 16, v11
	v_and_b32_e32 v13, 0xffff0000, v11
	v_lshlrev_b32_e32 v14, 16, v163
	v_and_b32_e32 v15, 0xffff0000, v163
	v_lshl_add_u64 v[4:5], v[4:5], 0, v[2:3]
	v_pk_mul_f32 v[12:13], v[14:15], v[12:13]
	s_waitcnt vmcnt(6)
	v_lshlrev_b32_e32 v14, 16, v156
	v_cvt_pk_bf16_f32 v11, v12, v13
	v_add_co_u32_e32 v12, vcc, s47, v4
	v_and_b32_e32 v15, 0xffff0000, v156
	s_nop 0
	v_addc_co_u32_e32 v13, vcc, 0, v5, vcc
	global_store_dwordx4 v[12:13], v[8:11], off offset:2048 sc1
	ds_read_b128 v[8:11], v6 offset:1088
	s_add_i32 s40, s40, s10
	s_add_i32 s14, s14, s28
	s_add_i32 s1, s1, s29
	s_cmpk_gt_i32 s40, 0xff
	s_waitcnt lgkmcnt(0)
	v_lshlrev_b32_e32 v12, 16, v8
	v_and_b32_e32 v13, 0xffff0000, v8
	v_pk_mul_f32 v[12:13], v[14:15], v[12:13]
	v_lshlrev_b32_e32 v14, 16, v157
	v_cvt_pk_bf16_f32 v8, v12, v13
	v_lshlrev_b32_e32 v12, 16, v9
	v_and_b32_e32 v13, 0xffff0000, v9
	v_and_b32_e32 v15, 0xffff0000, v157
	v_pk_mul_f32 v[12:13], v[14:15], v[12:13]
	v_lshlrev_b32_e32 v14, 16, v158
	v_cvt_pk_bf16_f32 v9, v12, v13
	v_lshlrev_b32_e32 v12, 16, v10
	v_and_b32_e32 v13, 0xffff0000, v10
	v_and_b32_e32 v15, 0xffff0000, v158
	v_pk_mul_f32 v[12:13], v[14:15], v[12:13]
	v_lshlrev_b32_e32 v14, 16, v159
	v_cvt_pk_bf16_f32 v10, v12, v13
	v_lshlrev_b32_e32 v12, 16, v11
	v_and_b32_e32 v13, 0xffff0000, v11
	v_and_b32_e32 v15, 0xffff0000, v159
	v_pk_mul_f32 v[12:13], v[14:15], v[12:13]
	s_waitcnt vmcnt(6)
	v_lshlrev_b32_e32 v14, 16, v152
	v_cvt_pk_bf16_f32 v11, v12, v13
	v_add_co_u32_e32 v12, vcc, s48, v4
	v_and_b32_e32 v15, 0xffff0000, v152
	s_nop 0
	v_addc_co_u32_e32 v13, vcc, 0, v5, vcc
	global_store_dwordx4 v[12:13], v[8:11], off offset:2048 sc1
	ds_read_b128 v[8:11], v6 offset:2176
	s_waitcnt lgkmcnt(0)
	v_lshlrev_b32_e32 v12, 16, v8
	v_and_b32_e32 v13, 0xffff0000, v8
	v_pk_mul_f32 v[12:13], v[14:15], v[12:13]
	v_lshlrev_b32_e32 v14, 16, v153
	v_cvt_pk_bf16_f32 v8, v12, v13
	v_lshlrev_b32_e32 v12, 16, v9
	v_and_b32_e32 v13, 0xffff0000, v9
	v_and_b32_e32 v15, 0xffff0000, v153
	v_pk_mul_f32 v[12:13], v[14:15], v[12:13]
	v_lshlrev_b32_e32 v14, 16, v154
	v_cvt_pk_bf16_f32 v9, v12, v13
	v_lshlrev_b32_e32 v12, 16, v10
	v_and_b32_e32 v13, 0xffff0000, v10
	v_and_b32_e32 v15, 0xffff0000, v154
	v_pk_mul_f32 v[12:13], v[14:15], v[12:13]
	v_lshlrev_b32_e32 v14, 16, v155
	v_cvt_pk_bf16_f32 v10, v12, v13
	v_lshlrev_b32_e32 v12, 16, v11
	v_and_b32_e32 v13, 0xffff0000, v11
	v_and_b32_e32 v15, 0xffff0000, v155
	v_pk_mul_f32 v[12:13], v[14:15], v[12:13]
	s_waitcnt vmcnt(6)
	v_lshlrev_b32_e32 v14, 16, v148
	v_cvt_pk_bf16_f32 v11, v12, v13
	v_add_co_u32_e32 v12, vcc, s49, v4
	v_and_b32_e32 v15, 0xffff0000, v148
	s_nop 0
	v_addc_co_u32_e32 v13, vcc, 0, v5, vcc
	global_store_dwordx4 v[12:13], v[8:11], off offset:2048 sc1
	ds_read_b128 v[8:11], v6 offset:3264
	s_waitcnt lgkmcnt(0)
	v_lshlrev_b32_e32 v12, 16, v8
	v_and_b32_e32 v13, 0xffff0000, v8
	v_pk_mul_f32 v[12:13], v[14:15], v[12:13]
	v_lshlrev_b32_e32 v14, 16, v149
	v_cvt_pk_bf16_f32 v8, v12, v13
	v_lshlrev_b32_e32 v12, 16, v9
	v_and_b32_e32 v13, 0xffff0000, v9
	v_and_b32_e32 v15, 0xffff0000, v149
	v_pk_mul_f32 v[12:13], v[14:15], v[12:13]
	v_lshlrev_b32_e32 v14, 16, v150
	v_cvt_pk_bf16_f32 v9, v12, v13
	v_lshlrev_b32_e32 v12, 16, v10
	v_and_b32_e32 v13, 0xffff0000, v10
	v_and_b32_e32 v15, 0xffff0000, v150
	v_pk_mul_f32 v[12:13], v[14:15], v[12:13]
	v_lshlrev_b32_e32 v14, 16, v151
	v_cvt_pk_bf16_f32 v10, v12, v13
	v_lshlrev_b32_e32 v12, 16, v11
	v_and_b32_e32 v13, 0xffff0000, v11
	v_and_b32_e32 v15, 0xffff0000, v151
	v_pk_mul_f32 v[12:13], v[14:15], v[12:13]
	s_waitcnt vmcnt(6)
	v_lshlrev_b32_e32 v14, 16, v144
	v_cvt_pk_bf16_f32 v11, v12, v13
	v_add_co_u32_e32 v12, vcc, s54, v4
	v_and_b32_e32 v15, 0xffff0000, v144
	s_nop 0
	v_addc_co_u32_e32 v13, vcc, 0, v5, vcc
	global_store_dwordx4 v[12:13], v[8:11], off offset:2048 sc1
	ds_read_b128 v[8:11], v6 offset:4352
	s_waitcnt lgkmcnt(0)
	v_lshlrev_b32_e32 v12, 16, v8
	v_and_b32_e32 v13, 0xffff0000, v8
	v_pk_mul_f32 v[12:13], v[14:15], v[12:13]
	v_lshlrev_b32_e32 v14, 16, v145
	v_cvt_pk_bf16_f32 v8, v12, v13
	v_lshlrev_b32_e32 v12, 16, v9
	v_and_b32_e32 v13, 0xffff0000, v9
	v_and_b32_e32 v15, 0xffff0000, v145
	v_pk_mul_f32 v[12:13], v[14:15], v[12:13]
	v_lshlrev_b32_e32 v14, 16, v146
	v_cvt_pk_bf16_f32 v9, v12, v13
	v_lshlrev_b32_e32 v12, 16, v10
	v_and_b32_e32 v13, 0xffff0000, v10
	v_and_b32_e32 v15, 0xffff0000, v146
	v_pk_mul_f32 v[12:13], v[14:15], v[12:13]
	v_lshlrev_b32_e32 v14, 16, v147
	v_cvt_pk_bf16_f32 v10, v12, v13
	v_lshlrev_b32_e32 v12, 16, v11
	v_and_b32_e32 v13, 0xffff0000, v11
	v_and_b32_e32 v15, 0xffff0000, v147
	v_pk_mul_f32 v[12:13], v[14:15], v[12:13]
	s_waitcnt vmcnt(6)
	v_lshlrev_b32_e32 v14, 16, v140
	v_cvt_pk_bf16_f32 v11, v12, v13
	v_add_co_u32_e32 v12, vcc, s94, v4
	v_and_b32_e32 v15, 0xffff0000, v140
	s_nop 0
	v_addc_co_u32_e32 v13, vcc, 0, v5, vcc
	global_store_dwordx4 v[12:13], v[8:11], off offset:2048 sc1
	ds_read_b128 v[8:11], v6 offset:5440
	s_waitcnt lgkmcnt(0)
	v_lshlrev_b32_e32 v12, 16, v8
	v_and_b32_e32 v13, 0xffff0000, v8
	v_pk_mul_f32 v[12:13], v[14:15], v[12:13]
	v_lshlrev_b32_e32 v14, 16, v141
	v_cvt_pk_bf16_f32 v8, v12, v13
	v_lshlrev_b32_e32 v12, 16, v9
	v_and_b32_e32 v13, 0xffff0000, v9
	v_and_b32_e32 v15, 0xffff0000, v141
	v_pk_mul_f32 v[12:13], v[14:15], v[12:13]
	v_lshlrev_b32_e32 v14, 16, v142
	v_cvt_pk_bf16_f32 v9, v12, v13
	v_lshlrev_b32_e32 v12, 16, v10
	v_and_b32_e32 v13, 0xffff0000, v10
	v_and_b32_e32 v15, 0xffff0000, v142
	v_pk_mul_f32 v[12:13], v[14:15], v[12:13]
	v_lshlrev_b32_e32 v14, 16, v143
	v_cvt_pk_bf16_f32 v10, v12, v13
	v_lshlrev_b32_e32 v12, 16, v11
	v_and_b32_e32 v13, 0xffff0000, v11
	v_and_b32_e32 v15, 0xffff0000, v143
	v_pk_mul_f32 v[12:13], v[14:15], v[12:13]
	s_waitcnt vmcnt(6)
	v_lshlrev_b32_e32 v14, 16, v136
	v_cvt_pk_bf16_f32 v11, v12, v13
	v_add_co_u32_e32 v12, vcc, s97, v4
	v_and_b32_e32 v15, 0xffff0000, v136
	s_nop 0
	v_addc_co_u32_e32 v13, vcc, 0, v5, vcc
	global_store_dwordx4 v[12:13], v[8:11], off offset:2048 sc1
	ds_read_b128 v[8:11], v6 offset:6528
	s_waitcnt lgkmcnt(0)
	v_lshlrev_b32_e32 v12, 16, v8
	v_and_b32_e32 v13, 0xffff0000, v8
	v_pk_mul_f32 v[12:13], v[14:15], v[12:13]
	v_lshlrev_b32_e32 v14, 16, v137
	v_cvt_pk_bf16_f32 v8, v12, v13
	v_lshlrev_b32_e32 v12, 16, v9
	v_and_b32_e32 v13, 0xffff0000, v9
	v_and_b32_e32 v15, 0xffff0000, v137
	v_pk_mul_f32 v[12:13], v[14:15], v[12:13]
	v_lshlrev_b32_e32 v14, 16, v138
	v_cvt_pk_bf16_f32 v9, v12, v13
	v_lshlrev_b32_e32 v12, 16, v10
	v_and_b32_e32 v13, 0xffff0000, v10
	v_and_b32_e32 v15, 0xffff0000, v138
	v_pk_mul_f32 v[12:13], v[14:15], v[12:13]
	v_lshlrev_b32_e32 v14, 16, v139
	v_cvt_pk_bf16_f32 v10, v12, v13
	v_lshlrev_b32_e32 v12, 16, v11
	v_and_b32_e32 v13, 0xffff0000, v11
	v_and_b32_e32 v15, 0xffff0000, v139
	v_pk_mul_f32 v[12:13], v[14:15], v[12:13]
	s_nop 0
	v_cvt_pk_bf16_f32 v11, v12, v13
	v_add_co_u32_e32 v12, vcc, s55, v4
	s_nop 1
	v_addc_co_u32_e32 v13, vcc, 0, v5, vcc
	global_store_dwordx4 v[12:13], v[8:11], off offset:2048 sc1
	ds_read_b128 v[6:9], v6 offset:7616
	s_waitcnt vmcnt(7)
	v_lshlrev_b32_e32 v12, 16, v132
	v_and_b32_e32 v13, 0xffff0000, v132
	v_add_co_u32_e32 v4, vcc, 0xc615000, v4
	s_waitcnt lgkmcnt(0)
	v_lshlrev_b32_e32 v10, 16, v6
	v_and_b32_e32 v11, 0xffff0000, v6
	v_pk_mul_f32 v[10:11], v[12:13], v[10:11]
	v_lshlrev_b32_e32 v12, 16, v133
	v_cvt_pk_bf16_f32 v6, v10, v11
	v_lshlrev_b32_e32 v10, 16, v7
	v_and_b32_e32 v11, 0xffff0000, v7
	v_and_b32_e32 v13, 0xffff0000, v133
	v_pk_mul_f32 v[10:11], v[12:13], v[10:11]
	v_lshlrev_b32_e32 v12, 16, v134
	v_cvt_pk_bf16_f32 v7, v10, v11
	v_lshlrev_b32_e32 v10, 16, v8
	v_and_b32_e32 v11, 0xffff0000, v8
	v_and_b32_e32 v13, 0xffff0000, v134
	v_pk_mul_f32 v[10:11], v[12:13], v[10:11]
	v_lshlrev_b32_e32 v12, 16, v135
	v_cvt_pk_bf16_f32 v8, v10, v11
	v_lshlrev_b32_e32 v10, 16, v9
	v_and_b32_e32 v11, 0xffff0000, v9
	v_and_b32_e32 v13, 0xffff0000, v135
	v_pk_mul_f32 v[10:11], v[12:13], v[10:11]
	v_addc_co_u32_e32 v5, vcc, 0, v5, vcc
	v_cvt_pk_bf16_f32 v9, v10, v11
	global_store_dwordx4 v[4:5], v[6:9], off offset:2048 sc1
	s_barrier
	s_cbranch_scc0 .LBB0_547

.LBB0_758:
	s_ashr_i32 s40, s43, 7
	s_lshl_b32 s24, s40, 8
	s_add_i32 s44, s24, s95
	s_ashr_i32 s45, s44, 31
	s_lshl_b64 s[44:45], s[44:45], 10
	s_add_u32 s41, s92, s44
	s_addc_u32 s47, s9, s45
	s_and_b32 s24, s42, 0x180
	s_lshl_b32 s24, s24, 1
	s_add_u32 s46, s41, s24
	s_addc_u32 s47, s47, 0
	v_mov_b32_e32 v211, v204
	s_add_u32 s41, s56, s44
	s_addc_u32 s45, s57, s45
	v_ashrrev_i32_e32 v62, 5, v211
	v_and_b32_e32 v69, -8, v62
	s_add_u32 s44, s41, s24
	v_and_b32_e32 v68, 0xff, v211
	v_lshlrev_b32_e32 v4, 3, v69
	s_addc_u32 s45, s45, 0
	v_lshlrev_b32_e32 v2, 10, v68
	v_ashrrev_i32_e32 v5, 31, v4
	v_or_b32_e32 v70, 1, v69
	v_lshl_add_u64 v[60:61], s[46:47], 0, v[2:3]
	v_lshl_add_u64 v[64:65], s[44:45], 0, v[2:3]
	v_lshlrev_b64 v[8:9], 1, v[4:5]
	v_lshlrev_b32_e32 v16, 3, v70
	v_or_b32_e32 v71, 2, v69
	v_or_b32_e32 v73, 4, v69
	v_lshl_add_u64 v[28:29], v[60:61], 0, v[8:9]
	v_lshl_add_u64 v[8:9], v[64:65], 0, v[8:9]
	v_ashrrev_i32_e32 v17, 31, v16
	v_lshlrev_b32_e32 v24, 3, v71
	v_or_b32_e32 v72, 3, v69
	v_lshlrev_b32_e32 v36, 3, v73
	global_load_dwordx4 v[4:7], v[28:29], off
	s_nop 0
	global_load_dwordx4 v[8:11], v[8:9], off
	s_nop 0
	global_load_dwordx4 v[12:15], v[28:29], off offset:16
	v_lshl_add_u64 v[16:17], v[16:17], 1, v[64:65]
	v_ashrrev_i32_e32 v25, 31, v24
	v_lshlrev_b32_e32 v32, 3, v72
	v_ashrrev_i32_e32 v37, 31, v36
	global_load_dwordx4 v[16:19], v[16:17], off
	s_nop 0
	global_load_dwordx4 v[20:23], v[28:29], off offset:32
	v_lshl_add_u64 v[24:25], v[24:25], 1, v[64:65]
	v_ashrrev_i32_e32 v33, 31, v32
	v_lshlrev_b64 v[40:41], 1, v[36:37]
	v_or_b32_e32 v74, 5, v69
	v_or_b32_e32 v75, 6, v69
	v_or_b32_e32 v76, 7, v62
	global_load_dwordx4 v[24:27], v[24:25], off
	s_nop 0
	global_load_dwordx4 v[28:31], v[28:29], off offset:48
	v_lshl_add_u64 v[32:33], v[32:33], 1, v[64:65]
	v_lshl_add_u64 v[52:53], v[60:61], 0, v[40:41]
	v_lshlrev_b32_e32 v48, 3, v74
	v_lshlrev_b32_e32 v56, 3, v75
	v_lshlrev_b32_e32 v62, 3, v76
	global_load_dwordx4 v[32:35], v[32:33], off
	v_lshl_add_u64 v[40:41], v[64:65], 0, v[40:41]
	global_load_dwordx4 v[36:39], v[52:53], off
	v_ashrrev_i32_e32 v49, 31, v48
	v_ashrrev_i32_e32 v57, 31, v56
	v_ashrrev_i32_e32 v63, 31, v62
	global_load_dwordx4 v[40:43], v[40:41], off
	v_lshl_add_u64 v[48:49], v[48:49], 1, v[64:65]
	global_load_dwordx4 v[44:47], v[52:53], off offset:16
	v_lshl_add_u64 v[56:57], v[56:57], 1, v[64:65]
	v_lshlrev_b64 v[66:67], 1, v[62:63]
	global_load_dwordx4 v[48:51], v[48:49], off
	v_lshl_add_u64 v[60:61], v[60:61], 0, v[66:67]
	global_load_dwordx4 v[56:59], v[56:57], off
	v_lshl_add_u64 v[64:65], v[64:65], 0, v[66:67]
	global_load_dwordx4 v[52:55], v[52:53], off offset:32
	v_mad_u32_u24 v77, v68, s31, 0
	global_load_dwordx4 v[60:63], v[60:61], off
	v_lshl_add_u32 v2, v68, 1, s11
	global_load_dwordx4 v[64:67], v[64:65], off
	v_lshl_add_u32 v78, v69, 4, v77
	v_mad_u64_u32 v[68:69], s[44:45], v69, s77, v[2:3]
	v_lshl_add_u32 v69, v70, 4, v77
	s_ashr_i32 s41, s40, 31
	s_lshl_b64 s[40:41], s[40:41], 13
	v_and_b32_e32 v213, 31, v211
	v_bfe_u32 v210, v211, 4, 2
	s_waitcnt vmcnt(15)
	ds_write_b128 v78, v[4:7]
	s_waitcnt vmcnt(14)
	ds_write_b16 v68, v8
	ds_write_b16_d16_hi v68, v8 offset:520
	ds_write_b16 v68, v9 offset:1040
	ds_write_b16_d16_hi v68, v9 offset:1560
	ds_write_b16 v68, v10 offset:2080
	ds_write_b16_d16_hi v68, v10 offset:2600
	ds_write_b16 v68, v11 offset:3120
	ds_write_b16_d16_hi v68, v11 offset:3640
	s_waitcnt vmcnt(13)
	ds_write_b128 v69, v[12:15]
	s_waitcnt vmcnt(12)
	ds_write_b16 v68, v16 offset:4160
	ds_write_b16_d16_hi v68, v16 offset:4680
	ds_write_b16 v68, v17 offset:5200
	ds_write_b16_d16_hi v68, v17 offset:5720
	ds_write_b16 v68, v18 offset:6240
	ds_write_b16_d16_hi v68, v18 offset:6760
	ds_write_b16 v68, v19 offset:7280
	ds_write_b16_d16_hi v68, v19 offset:7800
	v_lshl_add_u32 v4, v71, 4, v77
	s_waitcnt vmcnt(11)
	ds_write_b128 v4, v[20:23]
	s_waitcnt vmcnt(10)
	ds_write_b16 v68, v24 offset:8320
	ds_write_b16_d16_hi v68, v24 offset:8840
	ds_write_b16 v68, v25 offset:9360
	ds_write_b16_d16_hi v68, v25 offset:9880
	ds_write_b16 v68, v26 offset:10400
	ds_write_b16_d16_hi v68, v26 offset:10920
	ds_write_b16 v68, v27 offset:11440
	ds_write_b16_d16_hi v68, v27 offset:11960
	v_lshl_add_u32 v4, v72, 4, v77
	s_waitcnt vmcnt(9)
	ds_write_b128 v4, v[28:31]
	s_waitcnt vmcnt(8)
	ds_write_b16 v68, v32 offset:12480
	ds_write_b16_d16_hi v68, v32 offset:13000
	ds_write_b16 v68, v33 offset:13520
	ds_write_b16_d16_hi v68, v33 offset:14040
	ds_write_b16 v68, v34 offset:14560
	ds_write_b16_d16_hi v68, v34 offset:15080
	ds_write_b16 v68, v35 offset:15600
	ds_write_b16_d16_hi v68, v35 offset:16120
	v_lshl_add_u32 v4, v73, 4, v77
	s_waitcnt vmcnt(7)
	ds_write_b128 v4, v[36:39]
	s_waitcnt vmcnt(6)
	ds_write_b16 v68, v40 offset:16640
	ds_write_b16_d16_hi v68, v40 offset:17160
	ds_write_b16 v68, v41 offset:17680
	ds_write_b16_d16_hi v68, v41 offset:18200
	ds_write_b16 v68, v42 offset:18720
	ds_write_b16_d16_hi v68, v42 offset:19240
	ds_write_b16 v68, v43 offset:19760
	ds_write_b16_d16_hi v68, v43 offset:20280
	v_lshl_add_u32 v4, v74, 4, v77
	s_waitcnt vmcnt(5)
	ds_write_b128 v4, v[44:47]
	s_waitcnt vmcnt(4)
	ds_write_b16 v68, v48 offset:20800
	ds_write_b16_d16_hi v68, v48 offset:21320
	ds_write_b16 v68, v49 offset:21840
	ds_write_b16_d16_hi v68, v49 offset:22360
	ds_write_b16 v68, v50 offset:22880
	ds_write_b16_d16_hi v68, v50 offset:23400
	ds_write_b16 v68, v51 offset:23920
	ds_write_b16_d16_hi v68, v51 offset:24440
	v_lshl_add_u32 v4, v75, 4, v77
	s_waitcnt vmcnt(2)
	ds_write_b128 v4, v[52:55]
	ds_write_b16 v68, v56 offset:24960
	ds_write_b16_d16_hi v68, v56 offset:25480
	ds_write_b16 v68, v57 offset:26000
	ds_write_b16_d16_hi v68, v57 offset:26520
	ds_write_b16 v68, v58 offset:27040
	ds_write_b16_d16_hi v68, v58 offset:27560
	ds_write_b16 v68, v59 offset:28080
	ds_write_b16_d16_hi v68, v59 offset:28600
	v_lshl_add_u32 v4, v76, 4, v77
	s_waitcnt vmcnt(1)
	ds_write_b128 v4, v[60:63]
	v_mad_u64_u32 v[4:5], s[44:45], v76, s77, v[2:3]
	s_and_b32 s44, s14, 0x1f00
	s_add_u32 s44, s44, s89
	s_addc_u32 s45, 0, s60
	s_add_u32 s40, s44, s40
	s_waitcnt vmcnt(0)
	ds_write_b16 v4, v64
	ds_write_b16_d16_hi v4, v64 offset:520
	ds_write_b16 v4, v65 offset:1040
	ds_write_b16_d16_hi v4, v65 offset:1560
	ds_write_b16 v4, v66 offset:2080
	ds_write_b16_d16_hi v4, v66 offset:2600
	ds_write_b16 v4, v67 offset:3120
	ds_write_b16_d16_hi v4, v67 offset:3640
	v_or_b32_e32 v2, s40, v213
	v_mov_b64_e32 v[4:5], s[54:55]
	s_addc_u32 s41, s45, s41
	v_mad_u64_u32 v[4:5], s[44:45], v2, s16, v[4:5]
	v_lshrrev_b32_e32 v2, 2, v211
	v_mad_i32_i24 v5, s41, v238, v5
	v_and_b32_e32 v215, 8, v2
	v_lshl_add_u64 v[4:5], v[4:5], 0, s[24:25]
	v_lshlrev_b32_e32 v6, 1, v215
	v_mov_b32_e32 v7, v3
	v_lshl_add_u64 v[4:5], v[4:5], 0, v[6:7]
	v_add_co_u32_e32 v6, vcc, s17, v4
	s_waitcnt lgkmcnt(0)
	s_nop 0
	v_addc_co_u32_e32 v7, vcc, 0, v5, vcc
	s_barrier
	global_load_dwordx4 v[116:119], v[6:7], off
	v_lshl_add_u64 v[8:9], v[4:5], 0, s[64:65]
	global_load_dwordx4 v[188:191], v[8:9], off offset:32
	global_load_dwordx4 v[184:187], v[8:9], off offset:64
	global_load_dwordx4 v[180:183], v[8:9], off offset:96
	global_load_dwordx4 v[176:179], v[8:9], off offset:128
	global_load_dwordx4 v[168:171], v[8:9], off offset:160
	global_load_dwordx4 v[164:167], v[8:9], off offset:192
	s_mul_i32 s44, s41, 0x1800
	s_mul_hi_u32 s45, s40, 0x1800
	s_add_i32 s45, s45, s44
	s_mul_i32 s44, s40, 0x1800
	v_lshrrev_b32_e32 v2, 1, v211
	s_add_u32 s44, s54, s44
	v_and_b32_e32 v2, 16, v2
	v_mul_u32_u24_e32 v4, 0x110, v213
	s_addc_u32 s45, s55, s45
	v_add3_u32 v198, 0, v2, v4
	s_add_u32 s44, s44, s24
	v_mul_u32_u24_e32 v2, 0xc00, v210
	s_addc_u32 s45, s45, 0
	v_lshlrev_b32_e32 v2, 1, v2
	global_load_dwordx4 v[172:175], v[8:9], off offset:224
	v_lshl_add_u64 v[8:9], s[44:45], 0, v[2:3]
	v_lshlrev_b32_e32 v2, 4, v211
	v_and_b32_e32 v2, 0xf0, v2
	v_lshl_add_u64 v[8:9], v[8:9], 0, v[2:3]
	v_add_co_u32_e32 v10, vcc, s17, v8
	ds_read_b128 v[4:7], v198
	s_nop 0
	v_addc_co_u32_e32 v11, vcc, 0, v9, vcc
	v_add_co_u32_e32 v12, vcc, s20, v8
	s_nop 1
	v_addc_co_u32_e32 v13, vcc, 0, v9, vcc
	global_load_dwordx4 v[160:163], v[10:11], off offset:1024
	global_load_dwordx4 v[156:159], v[12:13], off offset:1024
	v_add_co_u32_e32 v10, vcc, s30, v8
	s_nop 1
	v_addc_co_u32_e32 v11, vcc, 0, v9, vcc
	v_add_co_u32_e32 v12, vcc, s63, v8
	s_nop 1
	v_addc_co_u32_e32 v13, vcc, 0, v9, vcc
	global_load_dwordx4 v[152:155], v[10:11], off offset:1024
	global_load_dwordx4 v[148:151], v[12:13], off offset:1024
	v_add_co_u32_e32 v10, vcc, s34, v8
	s_nop 1
	v_addc_co_u32_e32 v11, vcc, 0, v9, vcc
	v_add_co_u32_e32 v12, vcc, s35, v8
	s_nop 1
	v_addc_co_u32_e32 v13, vcc, 0, v9, vcc
	global_load_dwordx4 v[144:147], v[10:11], off offset:1024
	global_load_dwordx4 v[140:143], v[12:13], off offset:1024
	v_add_co_u32_e32 v10, vcc, s96, v8
	s_nop 1
	v_addc_co_u32_e32 v11, vcc, 0, v9, vcc
	v_add_co_u32_e32 v8, vcc, s0, v8
	s_nop 1
	v_addc_co_u32_e32 v9, vcc, 0, v9, vcc
	global_load_dwordx4 v[136:139], v[10:11], off offset:1024
	global_load_dwordx4 v[132:135], v[8:9], off offset:1024
	ds_read_b128 v[20:23], v198 offset:32
	s_waitcnt vmcnt(15) lgkmcnt(1)
	v_mfma_f32_32x32x16_bf16 v[4:19], v[4:7], v[116:119], 0
	s_waitcnt vmcnt(14) lgkmcnt(0)
	v_mfma_f32_32x32x16_bf16 v[4:19], v[20:23], v[188:191], v[4:19]
	ds_read_b128 v[20:23], v198 offset:64
	s_waitcnt vmcnt(13) lgkmcnt(0)
	v_mfma_f32_32x32x16_bf16 v[4:19], v[20:23], v[184:187], v[4:19]
	ds_read_b128 v[20:23], v198 offset:96
	s_waitcnt vmcnt(12) lgkmcnt(0)
	v_mfma_f32_32x32x16_bf16 v[4:19], v[20:23], v[180:183], v[4:19]
	ds_read_b128 v[20:23], v198 offset:128
	s_waitcnt vmcnt(11) lgkmcnt(0)
	v_mfma_f32_32x32x16_bf16 v[4:19], v[20:23], v[176:179], v[4:19]
	ds_read_b128 v[20:23], v198 offset:160
	s_waitcnt vmcnt(10) lgkmcnt(0)
	v_mfma_f32_32x32x16_bf16 v[4:19], v[20:23], v[168:171], v[4:19]
	ds_read_b128 v[20:23], v198 offset:192
	s_waitcnt vmcnt(9) lgkmcnt(0)
	v_mfma_f32_32x32x16_bf16 v[4:19], v[20:23], v[164:167], v[4:19]
	ds_read_b128 v[20:23], v198 offset:224
	s_waitcnt vmcnt(8) lgkmcnt(0)
	v_mfma_f32_32x32x16_bf16 v[4:19], v[20:23], v[172:175], v[4:19]
	ds_read_b128 v[20:23], v198 offset:8704
	ds_read_b128 v[36:39], v198 offset:8736
	ds_read_b128 v[40:43], v198 offset:8768
	ds_read_b128 v[44:47], v198 offset:8800
	ds_read_b128 v[48:51], v198 offset:8832
	s_waitcnt lgkmcnt(4)
	v_mfma_f32_32x32x16_bf16 v[20:35], v[20:23], v[116:119], 0
	s_waitcnt lgkmcnt(3)
	v_mfma_f32_32x32x16_bf16 v[20:35], v[36:39], v[188:191], v[20:35]
	ds_read_b128 v[36:39], v198 offset:8864
	s_waitcnt lgkmcnt(3)
	v_mfma_f32_32x32x16_bf16 v[20:35], v[40:43], v[184:187], v[20:35]
	ds_read_b128 v[40:43], v198 offset:8896
	s_waitcnt lgkmcnt(3)
	v_mfma_f32_32x32x16_bf16 v[20:35], v[44:47], v[180:183], v[20:35]
	ds_read_b128 v[44:47], v198 offset:8928
	s_waitcnt lgkmcnt(3)
	v_mfma_f32_32x32x16_bf16 v[20:35], v[48:51], v[176:179], v[20:35]
	s_waitcnt lgkmcnt(2)
	v_mfma_f32_32x32x16_bf16 v[20:35], v[36:39], v[168:171], v[20:35]
	s_waitcnt lgkmcnt(1)
	v_mfma_f32_32x32x16_bf16 v[20:35], v[40:43], v[164:167], v[20:35]
	s_waitcnt lgkmcnt(0)
	v_mfma_f32_32x32x16_bf16 v[20:35], v[44:47], v[172:175], v[20:35]
	ds_read_b128 v[36:39], v198 offset:17408
	ds_read_b128 v[52:55], v198 offset:17440
	ds_read_b128 v[56:59], v198 offset:17472
	ds_read_b128 v[60:63], v198 offset:17504
	ds_read_b128 v[64:67], v198 offset:17536
	v_or_b32_e32 v214, 64, v213
	s_waitcnt lgkmcnt(4)
	v_mfma_f32_32x32x16_bf16 v[36:51], v[36:39], v[116:119], 0
	s_waitcnt lgkmcnt(3)
	v_mfma_f32_32x32x16_bf16 v[36:51], v[52:55], v[188:191], v[36:51]
	ds_read_b128 v[52:55], v198 offset:17568
	s_waitcnt lgkmcnt(3)
	v_mfma_f32_32x32x16_bf16 v[36:51], v[56:59], v[184:187], v[36:51]
	ds_read_b128 v[56:59], v198 offset:17600
	s_waitcnt lgkmcnt(3)
	v_mfma_f32_32x32x16_bf16 v[36:51], v[60:63], v[180:183], v[36:51]
	ds_read_b128 v[60:63], v198 offset:17632
	s_waitcnt lgkmcnt(3)
	v_mfma_f32_32x32x16_bf16 v[36:51], v[64:67], v[176:179], v[36:51]
	s_waitcnt lgkmcnt(2)
	v_mfma_f32_32x32x16_bf16 v[36:51], v[52:55], v[168:171], v[36:51]
	s_waitcnt lgkmcnt(1)
	v_mfma_f32_32x32x16_bf16 v[36:51], v[56:59], v[164:167], v[36:51]
	s_waitcnt lgkmcnt(0)
	v_mfma_f32_32x32x16_bf16 v[36:51], v[60:63], v[172:175], v[36:51]
	ds_read_b128 v[52:55], v198 offset:26112
	ds_read_b128 v[68:71], v198 offset:26144
	ds_read_b128 v[72:75], v198 offset:26176
	ds_read_b128 v[76:79], v198 offset:26208
	ds_read_b128 v[80:83], v198 offset:26240
	v_or_b32_e32 v212, 0x60, v213
	s_waitcnt lgkmcnt(4)
	v_mfma_f32_32x32x16_bf16 v[52:67], v[52:55], v[116:119], 0
	s_waitcnt lgkmcnt(3)
	v_mfma_f32_32x32x16_bf16 v[52:67], v[68:71], v[188:191], v[52:67]
	ds_read_b128 v[68:71], v198 offset:26272
	s_waitcnt lgkmcnt(3)
	v_mfma_f32_32x32x16_bf16 v[52:67], v[72:75], v[184:187], v[52:67]
	ds_read_b128 v[72:75], v198 offset:26304
	s_waitcnt lgkmcnt(3)
	v_mfma_f32_32x32x16_bf16 v[52:67], v[76:79], v[180:183], v[52:67]
	ds_read_b128 v[76:79], v198 offset:26336
	s_waitcnt lgkmcnt(3)
	v_mfma_f32_32x32x16_bf16 v[52:67], v[80:83], v[176:179], v[52:67]
	s_waitcnt lgkmcnt(2)
	v_mfma_f32_32x32x16_bf16 v[52:67], v[68:71], v[168:171], v[52:67]
	s_waitcnt lgkmcnt(1)
	v_mfma_f32_32x32x16_bf16 v[52:67], v[72:75], v[164:167], v[52:67]
	s_waitcnt lgkmcnt(0)
	v_mfma_f32_32x32x16_bf16 v[52:67], v[76:79], v[172:175], v[52:67]
	ds_read_b128 v[68:71], v198 offset:34816
	ds_read_b128 v[84:87], v198 offset:34848
	ds_read_b128 v[88:91], v198 offset:34880
	ds_read_b128 v[92:95], v198 offset:34912
	ds_read_b128 v[96:99], v198 offset:34944
	s_waitcnt lgkmcnt(4)
	v_mfma_f32_32x32x16_bf16 v[68:83], v[68:71], v[116:119], 0
	s_waitcnt lgkmcnt(3)
	v_mfma_f32_32x32x16_bf16 v[68:83], v[84:87], v[188:191], v[68:83]
	ds_read_b128 v[84:87], v198 offset:34976
	s_waitcnt lgkmcnt(3)
	v_mfma_f32_32x32x16_bf16 v[68:83], v[88:91], v[184:187], v[68:83]
	ds_read_b128 v[88:91], v198 offset:35008
	s_waitcnt lgkmcnt(3)
	v_mfma_f32_32x32x16_bf16 v[68:83], v[92:95], v[180:183], v[68:83]
	ds_read_b128 v[92:95], v198 offset:35040
	s_waitcnt lgkmcnt(3)
	v_mfma_f32_32x32x16_bf16 v[68:83], v[96:99], v[176:179], v[68:83]
	s_waitcnt lgkmcnt(2)
	v_mfma_f32_32x32x16_bf16 v[68:83], v[84:87], v[168:171], v[68:83]
	s_waitcnt lgkmcnt(1)
	v_mfma_f32_32x32x16_bf16 v[68:83], v[88:91], v[164:167], v[68:83]
	s_waitcnt lgkmcnt(0)
	v_mfma_f32_32x32x16_bf16 v[68:83], v[92:95], v[172:175], v[68:83]
	ds_read_b128 v[84:87], v198 offset:43520
	ds_read_b128 v[100:103], v198 offset:43552
	ds_read_b128 v[104:107], v198 offset:43584
	ds_read_b128 v[108:111], v198 offset:43616
	ds_read_b128 v[112:115], v198 offset:43648
	s_waitcnt lgkmcnt(4)
	v_mfma_f32_32x32x16_bf16 v[84:99], v[84:87], v[116:119], 0
	s_waitcnt lgkmcnt(3)
	v_mfma_f32_32x32x16_bf16 v[84:99], v[100:103], v[188:191], v[84:99]
	ds_read_b128 v[100:103], v198 offset:43680
	s_waitcnt lgkmcnt(3)
	v_mfma_f32_32x32x16_bf16 v[84:99], v[104:107], v[184:187], v[84:99]
	ds_read_b128 v[104:107], v198 offset:43712
	s_waitcnt lgkmcnt(3)
	v_mfma_f32_32x32x16_bf16 v[84:99], v[108:111], v[180:183], v[84:99]
	ds_read_b128 v[108:111], v198 offset:43744
	s_waitcnt lgkmcnt(3)
	v_mfma_f32_32x32x16_bf16 v[84:99], v[112:115], v[176:179], v[84:99]
	s_waitcnt lgkmcnt(2)
	v_mfma_f32_32x32x16_bf16 v[84:99], v[100:103], v[168:171], v[84:99]
	s_waitcnt lgkmcnt(1)
	v_mfma_f32_32x32x16_bf16 v[84:99], v[104:107], v[164:167], v[84:99]
	s_waitcnt lgkmcnt(0)
	v_mfma_f32_32x32x16_bf16 v[84:99], v[108:111], v[172:175], v[84:99]
	ds_read_b128 v[100:103], v198 offset:52224
	ds_read_b128 v[120:123], v198 offset:52256
	ds_read_b128 v[124:127], v198 offset:52288
	ds_read_b128 v[128:131], v198 offset:52320
	s_waitcnt lgkmcnt(3)
	v_mfma_f32_32x32x16_bf16 v[100:115], v[100:103], v[116:119], 0
	s_waitcnt lgkmcnt(2)
	v_mfma_f32_32x32x16_bf16 v[100:115], v[120:123], v[188:191], v[100:115]
	ds_read_b128 v[120:123], v198 offset:52352
	s_waitcnt lgkmcnt(2)
	v_mfma_f32_32x32x16_bf16 v[100:115], v[124:127], v[184:187], v[100:115]
	ds_read_b128 v[124:127], v198 offset:52384
	s_waitcnt lgkmcnt(2)
	v_mfma_f32_32x32x16_bf16 v[100:115], v[128:131], v[180:183], v[100:115]
	ds_read_b128 v[128:131], v198 offset:52416
	s_waitcnt lgkmcnt(2)
	v_mfma_f32_32x32x16_bf16 v[100:115], v[120:123], v[176:179], v[100:115]
	ds_read_b128 v[120:123], v198 offset:52448
	s_waitcnt lgkmcnt(2)
	v_mfma_f32_32x32x16_bf16 v[100:115], v[124:127], v[168:171], v[100:115]
	s_waitcnt lgkmcnt(1)
	v_mfma_f32_32x32x16_bf16 v[100:115], v[128:131], v[164:167], v[100:115]
	s_waitcnt lgkmcnt(0)
	v_mfma_f32_32x32x16_bf16 v[100:115], v[120:123], v[172:175], v[100:115]
	ds_read_b128 v[120:123], v198 offset:60928
	ds_read_b128 v[200:203], v198 offset:60960
	s_waitcnt lgkmcnt(1)
	v_mfma_f32_32x32x16_bf16 v[116:131], v[120:123], v[116:119], 0
	s_waitcnt lgkmcnt(0)
	v_mfma_f32_32x32x16_bf16 v[116:131], v[200:203], v[188:191], v[116:131]
	ds_read_b128 v[188:191], v198 offset:60992
	s_waitcnt lgkmcnt(0)
	v_mfma_f32_32x32x16_bf16 v[116:131], v[188:191], v[184:187], v[116:131]
	ds_read_b128 v[184:187], v198 offset:61024
	s_waitcnt lgkmcnt(0)
	v_mfma_f32_32x32x16_bf16 v[116:131], v[184:187], v[180:183], v[116:131]
	ds_read_b128 v[180:183], v198 offset:61056
	s_waitcnt lgkmcnt(0)
	v_mfma_f32_32x32x16_bf16 v[116:131], v[180:183], v[176:179], v[116:131]
	ds_read_b128 v[176:179], v198 offset:61088
	s_waitcnt lgkmcnt(0)
	v_mfma_f32_32x32x16_bf16 v[116:131], v[176:179], v[168:171], v[116:131]
	ds_read_b128 v[168:171], v198 offset:61120
	s_waitcnt lgkmcnt(0)
	v_mfma_f32_32x32x16_bf16 v[116:131], v[168:171], v[164:167], v[116:131]
	ds_read_b128 v[164:167], v198 offset:61152
	s_waitcnt lgkmcnt(0)
	v_mfma_f32_32x32x16_bf16 v[116:131], v[164:167], v[172:175], v[116:131]
	v_max3_f32 v164, v4, s76, v5
	v_max3_f32 v164, v164, v6, v7
	v_max3_f32 v164, v164, v8, v9
	v_max3_f32 v164, v164, v10, v11
	v_max3_f32 v164, v164, v12, v13
	v_max3_f32 v164, v164, v14, v15
	v_max3_f32 v164, v164, v16, v17
	v_max3_f32 v164, v164, v18, v19
	v_max3_f32 v164, v164, v20, v21
	v_max3_f32 v164, v164, v22, v23
	v_max3_f32 v164, v164, v24, v25
	v_max3_f32 v164, v164, v26, v27
	v_max3_f32 v164, v164, v28, v29
	v_max3_f32 v164, v164, v30, v31
	v_max3_f32 v164, v164, v32, v33
	v_max3_f32 v164, v164, v34, v35
	v_max3_f32 v164, v164, v36, v37
	v_max3_f32 v164, v164, v38, v39
	v_max3_f32 v164, v164, v40, v41
	v_max3_f32 v164, v164, v42, v43
	v_max3_f32 v164, v164, v44, v45
	v_max3_f32 v164, v164, v46, v47
	v_max3_f32 v164, v164, v48, v49
	v_max3_f32 v164, v164, v50, v51
	v_max3_f32 v164, v164, v52, v53
	v_max3_f32 v164, v164, v54, v55
	v_max3_f32 v164, v164, v56, v57
	v_max3_f32 v164, v164, v58, v59
	v_max3_f32 v164, v164, v60, v61
	v_max3_f32 v164, v164, v62, v63
	v_max3_f32 v164, v164, v64, v65
	v_max3_f32 v164, v164, v66, v67
	v_max3_f32 v164, v164, v68, v69
	v_max3_f32 v164, v164, v70, v71
	v_max3_f32 v164, v164, v72, v73
	v_max3_f32 v164, v164, v74, v75
	v_max3_f32 v164, v164, v76, v77
	v_max3_f32 v164, v164, v78, v79
	v_max3_f32 v164, v164, v80, v81
	v_max3_f32 v164, v164, v82, v83
	v_max3_f32 v164, v164, v84, v85
	v_max3_f32 v164, v164, v86, v87
	v_max3_f32 v164, v164, v88, v89
	v_max3_f32 v164, v164, v90, v91
	v_max3_f32 v164, v164, v92, v93
	v_max3_f32 v164, v164, v94, v95
	v_max3_f32 v164, v164, v96, v97
	v_max3_f32 v164, v164, v98, v99
	v_max3_f32 v164, v164, v100, v101
	v_max3_f32 v164, v164, v102, v103
	v_max3_f32 v164, v164, v104, v105
	v_max3_f32 v164, v164, v106, v107
	v_max3_f32 v164, v164, v108, v109
	v_max3_f32 v164, v164, v110, v111
	v_max3_f32 v164, v164, v112, v113
	v_max3_f32 v164, v164, v114, v115
	v_max3_f32 v164, v164, v116, v117
	v_max3_f32 v164, v164, v118, v119
	v_max3_f32 v164, v164, v120, v121
	v_max3_f32 v164, v164, v122, v123
	v_max3_f32 v164, v164, v124, v125
	v_max3_f32 v164, v164, v126, v127
	v_max3_f32 v164, v164, v128, v129
	v_max3_f32 v164, v164, v130, v131
	ds_bpermute_b32 v165, v197, v164
	s_waitcnt lgkmcnt(0)
	s_barrier
	v_max_f32_e32 v165, v165, v165
	v_max_f32_e32 v216, v164, v165
	v_sub_f32_e32 v10, v10, v216
	v_exp_f32_e32 v164, v10
	v_sub_f32_e32 v10, v11, v216
	v_exp_f32_e32 v165, v10
	v_sub_f32_e32 v10, v12, v216
	v_exp_f32_e32 v166, v10
	v_sub_f32_e32 v10, v13, v216
	v_exp_f32_e32 v167, v10
	v_sub_f32_e32 v10, v14, v216
	v_exp_f32_e32 v168, v10
	v_sub_f32_e32 v10, v15, v216
	v_exp_f32_e32 v169, v10
	v_sub_f32_e32 v10, v16, v216
	v_exp_f32_e32 v170, v10
	v_sub_f32_e32 v10, v17, v216
	v_sub_f32_e32 v16, v26, v216
	v_exp_f32_e32 v171, v10
	v_sub_f32_e32 v10, v18, v216
	v_exp_f32_e32 v18, v16
	v_sub_f32_e32 v16, v27, v216
	v_exp_f32_e32 v172, v10
	v_sub_f32_e32 v10, v19, v216
	v_exp_f32_e32 v19, v16
	v_sub_f32_e32 v16, v28, v216
	v_exp_f32_e32 v28, v16
	v_sub_f32_e32 v16, v29, v216
	v_exp_f32_e32 v29, v16
	v_sub_f32_e32 v16, v30, v216
	v_exp_f32_e32 v30, v16
	v_sub_f32_e32 v16, v31, v216
	v_exp_f32_e32 v31, v16
	v_sub_f32_e32 v16, v32, v216
	v_exp_f32_e32 v32, v16
	v_sub_f32_e32 v16, v33, v216
	v_exp_f32_e32 v33, v16
	v_sub_f32_e32 v16, v34, v216
	v_exp_f32_e32 v173, v10
	v_sub_f32_e32 v10, v20, v216
	v_exp_f32_e32 v34, v16
	v_sub_f32_e32 v16, v35, v216
	v_sub_f32_e32 v20, v38, v216
	v_exp_f32_e32 v35, v16
	v_sub_f32_e32 v16, v36, v216
	v_exp_f32_e32 v36, v20
	v_sub_f32_e32 v20, v39, v216
	v_sub_f32_e32 v17, v37, v216
	v_exp_f32_e32 v37, v20
	v_sub_f32_e32 v20, v40, v216
	v_exp_f32_e32 v38, v20
	v_sub_f32_e32 v20, v41, v216
	v_exp_f32_e32 v39, v20
	v_sub_f32_e32 v20, v42, v216
	v_exp_f32_e32 v40, v20
	v_sub_f32_e32 v20, v43, v216
	v_exp_f32_e32 v41, v20
	v_sub_f32_e32 v20, v44, v216
	v_exp_f32_e32 v42, v20
	v_sub_f32_e32 v20, v45, v216
	v_exp_f32_e32 v43, v20
	v_sub_f32_e32 v20, v46, v216
	v_exp_f32_e32 v174, v20
	v_sub_f32_e32 v20, v47, v216
	v_exp_f32_e32 v175, v20
	v_sub_f32_e32 v20, v48, v216
	v_exp_f32_e32 v176, v20
	v_sub_f32_e32 v20, v49, v216
	v_exp_f32_e32 v177, v20
	v_sub_f32_e32 v20, v50, v216
	v_exp_f32_e32 v178, v20
	v_sub_f32_e32 v20, v51, v216
	v_exp_f32_e32 v179, v20
	v_sub_f32_e32 v20, v52, v216
	v_exp_f32_e32 v44, v20
	v_sub_f32_e32 v20, v53, v216
	v_exp_f32_e32 v45, v20
	v_sub_f32_e32 v20, v54, v216
	v_exp_f32_e32 v46, v20
	v_sub_f32_e32 v20, v55, v216
	v_exp_f32_e32 v47, v20
	v_sub_f32_e32 v20, v56, v216
	v_exp_f32_e32 v48, v20
	v_sub_f32_e32 v20, v57, v216
	v_exp_f32_e32 v49, v20
	v_sub_f32_e32 v20, v58, v216
	v_exp_f32_e32 v50, v20
	v_sub_f32_e32 v20, v59, v216
	v_exp_f32_e32 v51, v20
	v_sub_f32_e32 v20, v60, v216
	v_exp_f32_e32 v56, v20
	v_sub_f32_e32 v20, v61, v216
	v_exp_f32_e32 v57, v20
	v_sub_f32_e32 v20, v62, v216
	v_exp_f32_e32 v60, v20
	v_sub_f32_e32 v20, v63, v216
	v_exp_f32_e32 v61, v20
	v_sub_f32_e32 v20, v64, v216
	v_exp_f32_e32 v180, v20
	v_sub_f32_e32 v20, v65, v216
	v_exp_f32_e32 v181, v20
	v_sub_f32_e32 v20, v66, v216
	v_exp_f32_e32 v182, v20
	v_sub_f32_e32 v20, v67, v216
	v_exp_f32_e32 v183, v20
	v_sub_f32_e32 v20, v68, v216
	v_exp_f32_e32 v52, v20
	v_sub_f32_e32 v20, v69, v216
	v_exp_f32_e32 v53, v20
	v_sub_f32_e32 v20, v70, v216
	v_exp_f32_e32 v54, v20
	v_sub_f32_e32 v20, v71, v216
	v_exp_f32_e32 v55, v20
	v_sub_f32_e32 v20, v72, v216
	v_exp_f32_e32 v58, v20
	v_sub_f32_e32 v20, v73, v216
	v_exp_f32_e32 v59, v20
	v_sub_f32_e32 v20, v74, v216
	v_exp_f32_e32 v64, v20
	v_sub_f32_e32 v20, v75, v216
	v_exp_f32_e32 v65, v20
	v_sub_f32_e32 v20, v76, v216
	v_exp_f32_e32 v68, v20
	v_sub_f32_e32 v20, v77, v216
	v_exp_f32_e32 v69, v20
	v_sub_f32_e32 v20, v78, v216
	v_exp_f32_e32 v72, v20
	v_sub_f32_e32 v20, v79, v216
	v_exp_f32_e32 v73, v20
	v_sub_f32_e32 v20, v80, v216
	v_exp_f32_e32 v186, v20
	v_sub_f32_e32 v20, v81, v216
	v_exp_f32_e32 v187, v20
	v_sub_f32_e32 v20, v82, v216
	v_exp_f32_e32 v190, v20
	v_sub_f32_e32 v20, v83, v216
	v_exp_f32_e32 v191, v20
	v_sub_f32_e32 v20, v84, v216
	v_exp_f32_e32 v62, v20
	v_sub_f32_e32 v20, v85, v216
	v_exp_f32_e32 v63, v20
	v_sub_f32_e32 v20, v86, v216
	v_exp_f32_e32 v66, v20
	v_sub_f32_e32 v20, v87, v216
	v_exp_f32_e32 v67, v20
	v_sub_f32_e32 v20, v88, v216
	v_exp_f32_e32 v70, v20
	v_sub_f32_e32 v20, v89, v216
	v_exp_f32_e32 v71, v20
	v_sub_f32_e32 v20, v90, v216
	v_exp_f32_e32 v184, v20
	v_sub_f32_e32 v20, v91, v216
	v_exp_f32_e32 v185, v20
	v_sub_f32_e32 v20, v92, v216
	v_exp_f32_e32 v188, v20
	v_sub_f32_e32 v20, v93, v216
	v_exp_f32_e32 v189, v20
	v_sub_f32_e32 v20, v94, v216
	v_exp_f32_e32 v198, v20
	v_sub_f32_e32 v20, v95, v216
	v_exp_f32_e32 v199, v20
	v_sub_f32_e32 v20, v96, v216
	v_exp_f32_e32 v200, v20
	v_sub_f32_e32 v20, v97, v216
	v_exp_f32_e32 v201, v20
	v_sub_f32_e32 v20, v98, v216
	v_exp_f32_e32 v202, v20
	v_sub_f32_e32 v20, v99, v216
	v_exp_f32_e32 v203, v20
	v_sub_f32_e32 v20, v100, v216
	v_exp_f32_e32 v74, v20
	v_sub_f32_e32 v20, v101, v216
	v_exp_f32_e32 v75, v20
	v_sub_f32_e32 v20, v102, v216
	v_exp_f32_e32 v92, v20
	v_sub_f32_e32 v20, v103, v216
	v_exp_f32_e32 v93, v20
	v_sub_f32_e32 v20, v104, v216
	v_exp_f32_e32 v94, v20
	v_sub_f32_e32 v20, v105, v216
	v_exp_f32_e32 v95, v20
	v_sub_f32_e32 v20, v106, v216
	v_exp_f32_e32 v96, v20
	v_sub_f32_e32 v20, v107, v216
	v_exp_f32_e32 v97, v20
	v_sub_f32_e32 v20, v108, v216
	v_exp_f32_e32 v98, v20
	v_sub_f32_e32 v20, v109, v216
	v_exp_f32_e32 v99, v20
	v_sub_f32_e32 v20, v110, v216
	v_exp_f32_e32 v100, v20
	v_sub_f32_e32 v20, v111, v216
	v_exp_f32_e32 v101, v20
	v_sub_f32_e32 v20, v112, v216
	v_exp_f32_e32 v102, v20
	v_sub_f32_e32 v20, v113, v216
	v_exp_f32_e32 v103, v20
	v_sub_f32_e32 v20, v114, v216
	v_exp_f32_e32 v104, v20
	v_sub_f32_e32 v20, v115, v216
	v_exp_f32_e32 v105, v20
	v_sub_f32_e32 v20, v116, v216
	v_exp_f32_e32 v76, v20
	v_sub_f32_e32 v20, v117, v216
	v_exp_f32_e32 v77, v20
	v_sub_f32_e32 v20, v118, v216
	v_exp_f32_e32 v80, v20
	v_sub_f32_e32 v20, v119, v216
	v_exp_f32_e32 v81, v20
	v_sub_f32_e32 v20, v120, v216
	v_exp_f32_e32 v84, v20
	v_sub_f32_e32 v20, v121, v216
	v_exp_f32_e32 v85, v20
	v_sub_f32_e32 v20, v122, v216
	v_exp_f32_e32 v88, v20
	v_sub_f32_e32 v20, v123, v216
	v_exp_f32_e32 v89, v20
	v_sub_f32_e32 v20, v124, v216
	v_exp_f32_e32 v78, v20
	v_sub_f32_e32 v20, v125, v216
	v_exp_f32_e32 v79, v20
	v_sub_f32_e32 v20, v126, v216
	v_sub_f32_e32 v4, v4, v216
	v_exp_f32_e32 v82, v20
	v_sub_f32_e32 v20, v127, v216
	v_sub_f32_e32 v5, v5, v216
	v_exp_f32_e32 v4, v4
	v_exp_f32_e32 v83, v20
	v_sub_f32_e32 v20, v128, v216
	v_sub_f32_e32 v6, v6, v216
	v_exp_f32_e32 v5, v5
	v_exp_f32_e32 v86, v20
	v_sub_f32_e32 v20, v129, v216
	v_exp_f32_e32 v6, v6
	v_sub_f32_e32 v7, v7, v216
	v_exp_f32_e32 v87, v20
	v_sub_f32_e32 v20, v130, v216
	v_exp_f32_e32 v7, v7
	v_sub_f32_e32 v8, v8, v216
	v_exp_f32_e32 v90, v20
	v_sub_f32_e32 v20, v131, v216
	v_exp_f32_e32 v8, v8
	v_sub_f32_e32 v9, v9, v216
	v_exp_f32_e32 v91, v20
	v_add_f32_e32 v20, 0, v4
	v_exp_f32_e32 v9, v9
	v_add_f32_e32 v20, v5, v20
	v_add_f32_e32 v20, v6, v20
	v_add_f32_e32 v20, v7, v20
	v_add_f32_e32 v20, v8, v20
	v_add_f32_e32 v20, v9, v20
	v_add_f32_e32 v20, v164, v20
	v_add_f32_e32 v20, v165, v20
	v_add_f32_e32 v20, v166, v20
	v_add_f32_e32 v20, v167, v20
	v_add_f32_e32 v20, v168, v20
	v_add_f32_e32 v20, v169, v20
	v_exp_f32_e32 v10, v10
	v_sub_f32_e32 v11, v21, v216
	v_add_f32_e32 v20, v170, v20
	v_exp_f32_e32 v11, v11
	v_sub_f32_e32 v12, v22, v216
	v_add_f32_e32 v20, v171, v20
	v_exp_f32_e32 v12, v12
	v_sub_f32_e32 v13, v23, v216
	v_add_f32_e32 v20, v172, v20
	v_exp_f32_e32 v13, v13
	v_sub_f32_e32 v14, v24, v216
	v_add_f32_e32 v20, v173, v20
	v_exp_f32_e32 v14, v14
	v_sub_f32_e32 v15, v25, v216
	v_add_f32_e32 v20, v10, v20
	v_exp_f32_e32 v15, v15
	v_add_f32_e32 v20, v11, v20
	v_add_f32_e32 v20, v12, v20
	v_add_f32_e32 v20, v13, v20
	v_add_f32_e32 v20, v14, v20
	v_add_f32_e32 v20, v15, v20
	v_add_f32_e32 v20, v18, v20
	v_add_f32_e32 v20, v19, v20
	v_add_f32_e32 v20, v28, v20
	v_add_f32_e32 v20, v29, v20
	v_add_f32_e32 v20, v30, v20
	v_add_f32_e32 v20, v31, v20
	v_exp_f32_e32 v16, v16
	v_add_f32_e32 v20, v32, v20
	v_exp_f32_e32 v17, v17
	v_add_f32_e32 v20, v33, v20
	v_add_f32_e32 v20, v34, v20
	v_add_f32_e32 v20, v35, v20
	v_add_f32_e32 v20, v16, v20
	v_add_f32_e32 v20, v17, v20
	v_add_f32_e32 v20, v36, v20
	v_add_f32_e32 v20, v37, v20
	v_add_f32_e32 v20, v38, v20
	v_add_f32_e32 v20, v39, v20
	v_add_f32_e32 v20, v40, v20
	v_add_f32_e32 v20, v41, v20
	v_add_f32_e32 v20, v42, v20
	v_add_f32_e32 v20, v43, v20
	v_add_f32_e32 v20, v174, v20
	v_add_f32_e32 v20, v175, v20
	v_add_f32_e32 v20, v176, v20
	v_add_f32_e32 v20, v177, v20
	v_add_f32_e32 v20, v178, v20
	v_add_f32_e32 v20, v179, v20
	v_add_f32_e32 v20, v44, v20
	v_add_f32_e32 v20, v45, v20
	v_add_f32_e32 v20, v46, v20
	v_add_f32_e32 v20, v47, v20
	v_add_f32_e32 v20, v48, v20
	v_add_f32_e32 v20, v49, v20
	v_add_f32_e32 v20, v50, v20
	v_add_f32_e32 v20, v51, v20
	v_add_f32_e32 v20, v56, v20
	v_add_f32_e32 v20, v57, v20
	v_add_f32_e32 v20, v60, v20
	v_add_f32_e32 v20, v61, v20
	v_add_f32_e32 v20, v180, v20
	v_add_f32_e32 v20, v181, v20
	v_add_f32_e32 v20, v182, v20
	v_add_f32_e32 v20, v183, v20
	v_add_f32_e32 v20, v52, v20
	v_add_f32_e32 v20, v53, v20
	v_add_f32_e32 v20, v54, v20
	v_add_f32_e32 v20, v55, v20
	v_add_f32_e32 v20, v58, v20
	v_add_f32_e32 v20, v59, v20
	v_add_f32_e32 v20, v64, v20
	v_add_f32_e32 v20, v65, v20
	v_add_f32_e32 v20, v68, v20
	v_add_f32_e32 v20, v69, v20
	v_add_f32_e32 v20, v72, v20
	v_add_f32_e32 v20, v73, v20
	v_add_f32_e32 v20, v186, v20
	v_add_f32_e32 v20, v187, v20
	v_add_f32_e32 v20, v190, v20
	v_add_f32_e32 v20, v191, v20
	v_add_f32_e32 v20, v62, v20
	v_add_f32_e32 v20, v63, v20
	v_add_f32_e32 v20, v66, v20
	v_add_f32_e32 v20, v67, v20
	v_add_f32_e32 v20, v70, v20
	v_add_f32_e32 v20, v71, v20
	v_add_f32_e32 v20, v184, v20
	v_add_f32_e32 v20, v185, v20
	v_add_f32_e32 v20, v188, v20
	v_add_f32_e32 v20, v189, v20
	v_add_f32_e32 v20, v198, v20
	v_add_f32_e32 v20, v199, v20
	v_add_f32_e32 v20, v200, v20
	v_add_f32_e32 v20, v201, v20
	v_add_f32_e32 v20, v202, v20
	v_add_f32_e32 v20, v203, v20
	v_add_f32_e32 v20, v74, v20
	v_add_f32_e32 v20, v75, v20
	v_add_f32_e32 v20, v92, v20
	v_add_f32_e32 v20, v93, v20
	v_add_f32_e32 v20, v94, v20
	v_add_f32_e32 v20, v95, v20
	v_add_f32_e32 v20, v96, v20
	v_add_f32_e32 v20, v97, v20
	v_add_f32_e32 v20, v98, v20
	v_add_f32_e32 v20, v99, v20
	v_add_f32_e32 v20, v100, v20
	v_add_f32_e32 v20, v101, v20
	v_add_f32_e32 v20, v102, v20
	v_add_f32_e32 v20, v103, v20
	v_add_f32_e32 v20, v104, v20
	v_add_f32_e32 v20, v105, v20
	v_add_f32_e32 v20, v76, v20
	v_add_f32_e32 v20, v77, v20
	v_add_f32_e32 v20, v80, v20
	v_add_f32_e32 v20, v81, v20
	v_add_f32_e32 v20, v84, v20
	v_add_f32_e32 v20, v85, v20
	v_add_f32_e32 v20, v88, v20
	v_add_f32_e32 v20, v89, v20
	v_add_f32_e32 v20, v78, v20
	v_add_f32_e32 v20, v79, v20
	v_add_f32_e32 v20, v82, v20
	v_add_f32_e32 v20, v83, v20
	v_add_f32_e32 v20, v86, v20
	v_add_f32_e32 v20, v87, v20
	v_add_f32_e32 v20, v90, v20
	v_add_f32_e32 v20, v91, v20
	ds_bpermute_b32 v21, v197, v20
	s_waitcnt lgkmcnt(0)
	v_add_f32_e32 v20, v20, v21
	v_div_scale_f32 v21, s[44:45], v20, v20, 1.0
	v_rcp_f32_e32 v22, v21
	s_nop 0
	v_fma_f32 v23, -v21, v22, 1.0
	v_fmac_f32_e32 v22, v23, v22
	v_div_scale_f32 v23, vcc, 1.0, v20, 1.0
	v_mul_f32_e32 v24, v23, v22
	v_fma_f32 v25, -v21, v24, v23
	v_fmac_f32_e32 v24, v25, v22
	v_fma_f32 v21, -v21, v24, v23
	v_div_fmas_f32 v21, v21, v22, v24
	v_div_fixup_f32 v106, v21, v20, 1.0
	v_pk_mul_f32 v[6:7], v[6:7], v[106:107] op_sel_hi:[1,0]
	v_pk_mul_f32 v[4:5], v[4:5], v[106:107] op_sel_hi:[1,0]
	v_pk_mul_f32 v[8:9], v[8:9], v[106:107] op_sel_hi:[1,0]
	v_cvt_pk_bf16_f32 v21, v6, v7
	v_pk_mul_f32 v[6:7], v[12:13], v[106:107] op_sel_hi:[1,0]
	v_pk_mul_f32 v[24:25], v[164:165], v[106:107] op_sel_hi:[1,0]
	v_pk_mul_f32 v[108:109], v[168:169], v[106:107] op_sel_hi:[1,0]
	v_cvt_pk_bf16_f32 v20, v4, v5
	v_cvt_pk_bf16_f32 v22, v8, v9
	v_pk_mul_f32 v[4:5], v[10:11], v[106:107] op_sel_hi:[1,0]
	v_pk_mul_f32 v[8:9], v[14:15], v[106:107] op_sel_hi:[1,0]
	v_pk_mul_f32 v[10:11], v[18:19], v[106:107] op_sel_hi:[1,0]
	v_pk_mul_f32 v[18:19], v[32:33], v[106:107] op_sel_hi:[1,0]
	v_cvt_pk_bf16_f32 v33, v6, v7
	v_pk_mul_f32 v[6:7], v[36:37], v[106:107] op_sel_hi:[1,0]
	v_cvt_pk_bf16_f32 v23, v24, v25
	v_cvt_pk_bf16_f32 v25, v108, v109
	v_pk_mul_f32 v[108:109], v[34:35], v[106:107] op_sel_hi:[1,0]
	v_cvt_pk_bf16_f32 v32, v4, v5
	v_cvt_pk_bf16_f32 v34, v8, v9
	v_pk_mul_f32 v[4:5], v[16:17], v[106:107] op_sel_hi:[1,0]
	v_pk_mul_f32 v[8:9], v[38:39], v[106:107] op_sel_hi:[1,0]
	v_cvt_pk_bf16_f32 v37, v6, v7
	v_pk_mul_f32 v[6:7], v[46:47], v[106:107] op_sel_hi:[1,0]
	v_cvt_pk_bf16_f32 v35, v10, v11
	v_pk_mul_f32 v[10:11], v[40:41], v[106:107] op_sel_hi:[1,0]
	v_cvt_pk_bf16_f32 v36, v4, v5
	v_cvt_pk_bf16_f32 v38, v8, v9
	v_pk_mul_f32 v[4:5], v[44:45], v[106:107] op_sel_hi:[1,0]
	v_pk_mul_f32 v[8:9], v[48:49], v[106:107] op_sel_hi:[1,0]
	v_cvt_pk_bf16_f32 v49, v6, v7
	v_pk_mul_f32 v[6:7], v[54:55], v[106:107] op_sel_hi:[1,0]
	v_pk_mul_f32 v[12:13], v[28:29], v[106:107] op_sel_hi:[1,0]
	v_cvt_pk_bf16_f32 v39, v10, v11
	v_pk_mul_f32 v[10:11], v[50:51], v[106:107] op_sel_hi:[1,0]
	v_cvt_pk_bf16_f32 v48, v4, v5
	v_pk_mul_f32 v[4:5], v[52:53], v[106:107] op_sel_hi:[1,0]
	v_cvt_pk_bf16_f32 v53, v6, v7
	v_pk_mul_f32 v[6:7], v[66:67], v[106:107] op_sel_hi:[1,0]
	v_cvt_pk_bf16_f32 v28, v12, v13
	v_pk_mul_f32 v[12:13], v[42:43], v[106:107] op_sel_hi:[1,0]
	v_cvt_pk_bf16_f32 v51, v10, v11
	v_pk_mul_f32 v[10:11], v[64:65], v[106:107] op_sel_hi:[1,0]
	v_cvt_pk_bf16_f32 v52, v4, v5
	v_pk_mul_f32 v[4:5], v[62:63], v[106:107] op_sel_hi:[1,0]
	v_cvt_pk_bf16_f32 v65, v6, v7
	v_pk_mul_f32 v[6:7], v[92:93], v[106:107] op_sel_hi:[1,0]
	v_add_u32_e32 v92, s11, v215
	v_pk_mul_f32 v[14:15], v[30:31], v[106:107] op_sel_hi:[1,0]
	v_cvt_pk_bf16_f32 v40, v12, v13
	v_pk_mul_f32 v[12:13], v[56:57], v[106:107] op_sel_hi:[1,0]
	v_cvt_pk_bf16_f32 v64, v4, v5
	v_pk_mul_f32 v[4:5], v[74:75], v[106:107] op_sel_hi:[1,0]
	v_mad_u32_u24 v93, v213, s8, v92
	v_cvt_pk_bf16_f32 v29, v14, v15
	v_cvt_pk_bf16_f32 v30, v18, v19
	v_pk_mul_f32 v[14:15], v[174:175], v[106:107] op_sel_hi:[1,0]
	v_pk_mul_f32 v[16:17], v[176:177], v[106:107] op_sel_hi:[1,0]
	v_pk_mul_f32 v[18:19], v[178:179], v[106:107] op_sel_hi:[1,0]
	v_cvt_pk_bf16_f32 v44, v12, v13
	v_pk_mul_f32 v[12:13], v[68:69], v[106:107] op_sel_hi:[1,0]
	v_cvt_pk_bf16_f32 v68, v4, v5
	v_cvt_pk_bf16_f32 v69, v6, v7
	ds_read2_b64 v[4:7], v93 offset1:2
	v_cvt_pk_bf16_f32 v41, v14, v15
	v_cvt_pk_bf16_f32 v42, v16, v17
	v_cvt_pk_bf16_f32 v43, v18, v19
	v_pk_mul_f32 v[14:15], v[60:61], v[106:107] op_sel_hi:[1,0]
	v_pk_mul_f32 v[16:17], v[180:181], v[106:107] op_sel_hi:[1,0]
	v_pk_mul_f32 v[18:19], v[182:183], v[106:107] op_sel_hi:[1,0]
	v_cvt_pk_bf16_f32 v50, v8, v9
	v_cvt_pk_bf16_f32 v45, v14, v15
	v_cvt_pk_bf16_f32 v46, v16, v17
	v_cvt_pk_bf16_f32 v47, v18, v19
	v_pk_mul_f32 v[8:9], v[58:59], v[106:107] op_sel_hi:[1,0]
	v_pk_mul_f32 v[14:15], v[72:73], v[106:107] op_sel_hi:[1,0]
	v_pk_mul_f32 v[16:17], v[186:187], v[106:107] op_sel_hi:[1,0]
	v_pk_mul_f32 v[18:19], v[190:191], v[106:107] op_sel_hi:[1,0]
	v_cvt_pk_bf16_f32 v54, v8, v9
	v_cvt_pk_bf16_f32 v55, v10, v11
	v_cvt_pk_bf16_f32 v56, v12, v13
	v_cvt_pk_bf16_f32 v57, v14, v15
	v_cvt_pk_bf16_f32 v58, v16, v17
	v_cvt_pk_bf16_f32 v59, v18, v19
	v_pk_mul_f32 v[8:9], v[70:71], v[106:107] op_sel_hi:[1,0]
	v_pk_mul_f32 v[10:11], v[184:185], v[106:107] op_sel_hi:[1,0]
	v_pk_mul_f32 v[12:13], v[188:189], v[106:107] op_sel_hi:[1,0]
	v_pk_mul_f32 v[14:15], v[198:199], v[106:107] op_sel_hi:[1,0]
	v_pk_mul_f32 v[16:17], v[200:201], v[106:107] op_sel_hi:[1,0]
	v_pk_mul_f32 v[18:19], v[202:203], v[106:107] op_sel_hi:[1,0]
	v_cvt_pk_bf16_f32 v66, v8, v9
	v_cvt_pk_bf16_f32 v67, v10, v11
	v_cvt_pk_bf16_f32 v60, v12, v13
	v_cvt_pk_bf16_f32 v61, v14, v15
	v_cvt_pk_bf16_f32 v62, v16, v17
	v_cvt_pk_bf16_f32 v63, v18, v19
	v_pk_mul_f32 v[8:9], v[94:95], v[106:107] op_sel_hi:[1,0]
	v_pk_mul_f32 v[10:11], v[96:97], v[106:107] op_sel_hi:[1,0]
	v_pk_mul_f32 v[12:13], v[98:99], v[106:107] op_sel_hi:[1,0]
	v_pk_mul_f32 v[14:15], v[100:101], v[106:107] op_sel_hi:[1,0]
	v_pk_mul_f32 v[16:17], v[102:103], v[106:107] op_sel_hi:[1,0]
	v_pk_mul_f32 v[18:19], v[104:105], v[106:107] op_sel_hi:[1,0]
	v_cvt_pk_bf16_f32 v70, v8, v9
	v_cvt_pk_bf16_f32 v71, v10, v11
	v_cvt_pk_bf16_f32 v72, v12, v13
	v_cvt_pk_bf16_f32 v73, v14, v15
	v_cvt_pk_bf16_f32 v74, v16, v17
	v_cvt_pk_bf16_f32 v75, v18, v19
	s_waitcnt lgkmcnt(0)
	v_mfma_f32_32x32x16_bf16 v[4:19], v[20:23], v[4:7], 0
	v_mul_f32_e64 v26, v166, v106
	v_mul_f32_e64 v27, v167, v106
	v_mul_f32_e64 v110, v170, v106
	v_mul_f32_e64 v111, v171, v106
	v_mul_f32_e64 v112, v172, v106
	v_mul_f32_e64 v113, v173, v106
	v_cvt_pk_bf16_f32 v24, v26, v27
	v_cvt_pk_bf16_f32 v26, v110, v111
	v_cvt_pk_bf16_f32 v27, v112, v113
	v_pk_mul_f32 v[94:95], v[80:81], v[106:107] op_sel_hi:[1,0]
	v_pk_mul_f32 v[96:97], v[78:79], v[106:107] op_sel_hi:[1,0]
	ds_read2_b64 v[78:81], v93 offset0:4 offset1:6
	s_waitcnt lgkmcnt(0)
	v_mfma_f32_32x32x16_bf16 v[4:19], v[24:27], v[78:81], v[4:19]
	v_mul_f32_e64 v84, v84, v106
	v_mul_f32_e64 v85, v85, v106
	v_mul_f32_e64 v98, v86, v106
	v_mul_f32_e64 v99, v87, v106
	v_cvt_pk_bf16_f32 v78, v84, v85
	ds_read2_b64 v[84:87], v93 offset0:8 offset1:10
	v_pk_mul_f32 v[88:89], v[88:89], v[106:107] op_sel_hi:[1,0]
	v_cvt_pk_bf16_f32 v31, v108, v109
	v_cvt_pk_bf16_f32 v79, v88, v89
	s_waitcnt lgkmcnt(0)
	v_mfma_f32_32x32x16_bf16 v[4:19], v[32:35], v[84:87], v[4:19]
	ds_read2_b64 v[86:89], v93 offset0:12 offset1:14
	v_lshrrev_b32_e32 v84, 3, v211
	v_and_b32_e32 v84, 4, v84
	v_lshlrev_b32_e32 v85, 1, v211
	v_mul_f32_e64 v76, v76, v106
	v_mul_f32_e64 v77, v77, v106
	v_pk_mul_f32 v[82:83], v[82:83], v[106:107] op_sel_hi:[1,0]
	v_pk_mul_f32 v[90:91], v[90:91], v[106:107] op_sel_hi:[1,0]
	v_mul_u32_u24_e32 v84, 0x110, v84
	v_and_b32_e32 v85, 62, v85
	v_cvt_pk_bf16_f32 v76, v76, v77
	v_cvt_pk_bf16_f32 v77, v94, v95
	v_cvt_pk_bf16_f32 v80, v96, v97
	v_cvt_pk_bf16_f32 v81, v82, v83
	v_cvt_pk_bf16_f32 v82, v98, v99
	v_cvt_pk_bf16_f32 v83, v90, v91
	v_add3_u32 v84, s61, v84, v85
	s_waitcnt lgkmcnt(0)
	v_mfma_f32_32x32x16_bf16 v[4:19], v[28:31], v[86:89], v[4:19]
	ds_read2_b64 v[86:89], v93 offset0:16 offset1:18
	s_waitcnt lgkmcnt(0)
	v_mfma_f32_32x32x16_bf16 v[4:19], v[36:39], v[86:89], v[4:19]
	ds_read2_b64 v[86:89], v93 offset0:20 offset1:22
	s_waitcnt lgkmcnt(0)
	v_mfma_f32_32x32x16_bf16 v[4:19], v[40:43], v[86:89], v[4:19]
	ds_read2_b64 v[86:89], v93 offset0:24 offset1:26
	s_waitcnt lgkmcnt(0)
	v_mfma_f32_32x32x16_bf16 v[4:19], v[48:51], v[86:89], v[4:19]
	ds_read2_b64 v[86:89], v93 offset0:28 offset1:30
	s_waitcnt lgkmcnt(0)
	v_mfma_f32_32x32x16_bf16 v[4:19], v[44:47], v[86:89], v[4:19]
	ds_read2_b64 v[86:89], v93 offset0:32 offset1:34
	s_waitcnt lgkmcnt(0)
	v_mfma_f32_32x32x16_bf16 v[4:19], v[52:55], v[86:89], v[4:19]
	ds_read2_b64 v[86:89], v93 offset0:36 offset1:38
	s_waitcnt lgkmcnt(0)
	v_mfma_f32_32x32x16_bf16 v[4:19], v[56:59], v[86:89], v[4:19]
	ds_read2_b64 v[86:89], v93 offset0:40 offset1:42
	s_waitcnt lgkmcnt(0)
	v_mfma_f32_32x32x16_bf16 v[4:19], v[64:67], v[86:89], v[4:19]
	ds_read2_b64 v[86:89], v93 offset0:44 offset1:46
	s_waitcnt lgkmcnt(0)
	v_mfma_f32_32x32x16_bf16 v[4:19], v[60:63], v[86:89], v[4:19]
	ds_read2_b64 v[86:89], v93 offset0:48 offset1:50
	s_waitcnt lgkmcnt(0)
	v_mfma_f32_32x32x16_bf16 v[4:19], v[68:71], v[86:89], v[4:19]
	ds_read2_b64 v[86:89], v93 offset0:52 offset1:54
	s_waitcnt lgkmcnt(0)
	v_mfma_f32_32x32x16_bf16 v[4:19], v[72:75], v[86:89], v[4:19]
	ds_read2_b64 v[86:89], v93 offset0:56 offset1:58
	s_waitcnt lgkmcnt(0)
	v_mfma_f32_32x32x16_bf16 v[4:19], v[76:79], v[86:89], v[4:19]
	ds_read2_b64 v[86:89], v93 offset0:60 offset1:62
	s_waitcnt lgkmcnt(0)
	v_mfma_f32_32x32x16_bf16 v[4:19], v[80:83], v[86:89], v[4:19]
	s_nop 11
	v_cvt_pk_bf16_f32 v4, v4, v5
	ds_write_b16 v84, v4
	ds_write_b16_d16_hi v84, v4 offset:272
	v_cvt_pk_bf16_f32 v4, v6, v7
	ds_write_b16 v84, v4 offset:544
	ds_write_b16_d16_hi v84, v4 offset:816
	v_cvt_pk_bf16_f32 v4, v8, v9
	ds_write_b16 v84, v4 offset:2176
	ds_write_b16_d16_hi v84, v4 offset:2448
	v_cvt_pk_bf16_f32 v4, v10, v11
	ds_write_b16 v84, v4 offset:2720
	ds_write_b16_d16_hi v84, v4 offset:2992
	v_cvt_pk_bf16_f32 v4, v12, v13
	ds_write_b16 v84, v4 offset:4352
	ds_write_b16_d16_hi v84, v4 offset:4624
	v_cvt_pk_bf16_f32 v4, v14, v15
	ds_write_b16 v84, v4 offset:4896
	ds_write_b16_d16_hi v84, v4 offset:5168
	v_cvt_pk_bf16_f32 v4, v16, v17
	ds_write_b16 v84, v4 offset:6528
	ds_write_b16_d16_hi v84, v4 offset:6800
	v_cvt_pk_bf16_f32 v4, v18, v19
	ds_write_b16 v84, v4 offset:7072
	ds_write_b16_d16_hi v84, v4 offset:7344
	v_add_u32_e32 v85, 0x4000, v93
	ds_read2_b64 v[4:7], v85 offset0:32 offset1:34
	ds_read2_b64 v[86:89], v85 offset0:36 offset1:38
	ds_read2_b64 v[94:97], v85 offset0:40 offset1:42
	ds_read2_b64 v[98:101], v85 offset0:44 offset1:46
	ds_read2_b64 v[102:105], v85 offset0:48 offset1:50
	s_waitcnt lgkmcnt(4)
	v_mfma_f32_32x32x16_bf16 v[4:19], v[20:23], v[4:7], 0
	s_waitcnt lgkmcnt(3)
	v_mfma_f32_32x32x16_bf16 v[4:19], v[24:27], v[86:89], v[4:19]
	ds_read2_b64 v[86:89], v85 offset0:52 offset1:54
	s_waitcnt lgkmcnt(3)
	v_mfma_f32_32x32x16_bf16 v[4:19], v[32:35], v[94:97], v[4:19]
	ds_read2_b64 v[94:97], v85 offset0:56 offset1:58
	s_waitcnt lgkmcnt(3)
	v_mfma_f32_32x32x16_bf16 v[4:19], v[28:31], v[98:101], v[4:19]
	ds_read2_b64 v[98:101], v85 offset0:60 offset1:62
	s_waitcnt lgkmcnt(3)
	v_mfma_f32_32x32x16_bf16 v[4:19], v[36:39], v[102:105], v[4:19]
	ds_read2_b64 v[102:105], v85 offset0:64 offset1:66
	s_waitcnt lgkmcnt(3)
	v_mfma_f32_32x32x16_bf16 v[4:19], v[40:43], v[86:89], v[4:19]
	ds_read2_b64 v[86:89], v85 offset0:68 offset1:70
	s_waitcnt lgkmcnt(3)
	v_mfma_f32_32x32x16_bf16 v[4:19], v[48:51], v[94:97], v[4:19]
	ds_read2_b64 v[94:97], v85 offset0:72 offset1:74
	s_waitcnt lgkmcnt(3)
	v_mfma_f32_32x32x16_bf16 v[4:19], v[44:47], v[98:101], v[4:19]
	ds_read2_b64 v[98:101], v85 offset0:76 offset1:78
	s_waitcnt lgkmcnt(3)
	v_mfma_f32_32x32x16_bf16 v[4:19], v[52:55], v[102:105], v[4:19]
	ds_read2_b64 v[102:105], v85 offset0:80 offset1:82
	s_waitcnt lgkmcnt(3)
	v_mfma_f32_32x32x16_bf16 v[4:19], v[56:59], v[86:89], v[4:19]
	ds_read2_b64 v[86:89], v85 offset0:84 offset1:86
	s_waitcnt lgkmcnt(3)
	v_mfma_f32_32x32x16_bf16 v[4:19], v[64:67], v[94:97], v[4:19]
	ds_read2_b64 v[94:97], v85 offset0:88 offset1:90
	s_waitcnt lgkmcnt(3)
	v_mfma_f32_32x32x16_bf16 v[4:19], v[60:63], v[98:101], v[4:19]
	ds_read2_b64 v[98:101], v85 offset0:92 offset1:94
	s_waitcnt lgkmcnt(3)
	v_mfma_f32_32x32x16_bf16 v[4:19], v[68:71], v[102:105], v[4:19]
	s_waitcnt lgkmcnt(2)
	v_mfma_f32_32x32x16_bf16 v[4:19], v[72:75], v[86:89], v[4:19]
	s_waitcnt lgkmcnt(1)
	v_mfma_f32_32x32x16_bf16 v[4:19], v[76:79], v[94:97], v[4:19]
	s_waitcnt lgkmcnt(0)
	v_mfma_f32_32x32x16_bf16 v[4:19], v[80:83], v[98:101], v[4:19]
	s_nop 11
	v_cvt_pk_bf16_f32 v4, v4, v5
	ds_write_b16 v84, v4 offset:64
	ds_write_b16_d16_hi v84, v4 offset:336
	v_cvt_pk_bf16_f32 v4, v6, v7
	ds_write_b16 v84, v4 offset:608
	ds_write_b16_d16_hi v84, v4 offset:880
	v_cvt_pk_bf16_f32 v4, v8, v9
	ds_write_b16 v84, v4 offset:2240
	ds_write_b16_d16_hi v84, v4 offset:2512
	v_cvt_pk_bf16_f32 v4, v10, v11
	ds_write_b16 v84, v4 offset:2784
	ds_write_b16_d16_hi v84, v4 offset:3056
	v_cvt_pk_bf16_f32 v4, v12, v13
	ds_write_b16 v84, v4 offset:4416
	ds_write_b16_d16_hi v84, v4 offset:4688
	v_cvt_pk_bf16_f32 v4, v14, v15
	ds_write_b16 v84, v4 offset:4960
	ds_write_b16_d16_hi v84, v4 offset:5232
	v_cvt_pk_bf16_f32 v4, v16, v17
	ds_write_b16 v84, v4 offset:6592
	ds_write_b16_d16_hi v84, v4 offset:6864
	v_cvt_pk_bf16_f32 v4, v18, v19
	ds_write_b16 v84, v4 offset:7136
	ds_write_b16_d16_hi v84, v4 offset:7408
	v_mad_u32_u24 v85, v214, s8, v92
	ds_read2_b64 v[4:7], v85 offset1:2
	ds_read2_b64 v[86:89], v85 offset0:4 offset1:6
	ds_read2_b64 v[94:97], v85 offset0:8 offset1:10
	ds_read2_b64 v[98:101], v85 offset0:12 offset1:14
	ds_read2_b64 v[102:105], v85 offset0:16 offset1:18
	s_waitcnt lgkmcnt(4)
	v_mfma_f32_32x32x16_bf16 v[4:19], v[20:23], v[4:7], 0
	s_waitcnt lgkmcnt(3)
	v_mfma_f32_32x32x16_bf16 v[4:19], v[24:27], v[86:89], v[4:19]
	ds_read2_b64 v[86:89], v85 offset0:20 offset1:22
	s_waitcnt lgkmcnt(3)
	v_mfma_f32_32x32x16_bf16 v[4:19], v[32:35], v[94:97], v[4:19]
	ds_read2_b64 v[94:97], v85 offset0:24 offset1:26
	s_waitcnt lgkmcnt(3)
	v_mfma_f32_32x32x16_bf16 v[4:19], v[28:31], v[98:101], v[4:19]
	ds_read2_b64 v[98:101], v85 offset0:28 offset1:30
	s_waitcnt lgkmcnt(3)
	v_mfma_f32_32x32x16_bf16 v[4:19], v[36:39], v[102:105], v[4:19]
	ds_read2_b64 v[102:105], v85 offset0:32 offset1:34
	s_waitcnt lgkmcnt(3)
	v_mfma_f32_32x32x16_bf16 v[4:19], v[40:43], v[86:89], v[4:19]
	ds_read2_b64 v[86:89], v85 offset0:36 offset1:38
	s_waitcnt lgkmcnt(3)
	v_mfma_f32_32x32x16_bf16 v[4:19], v[48:51], v[94:97], v[4:19]
	ds_read2_b64 v[94:97], v85 offset0:40 offset1:42
	s_waitcnt lgkmcnt(3)
	v_mfma_f32_32x32x16_bf16 v[4:19], v[44:47], v[98:101], v[4:19]
	ds_read2_b64 v[98:101], v85 offset0:44 offset1:46
	s_waitcnt lgkmcnt(3)
	v_mfma_f32_32x32x16_bf16 v[4:19], v[52:55], v[102:105], v[4:19]
	ds_read2_b64 v[102:105], v85 offset0:48 offset1:50
	s_waitcnt lgkmcnt(3)
	v_mfma_f32_32x32x16_bf16 v[4:19], v[56:59], v[86:89], v[4:19]
	ds_read2_b64 v[86:89], v85 offset0:52 offset1:54
	s_waitcnt lgkmcnt(3)
	v_mfma_f32_32x32x16_bf16 v[4:19], v[64:67], v[94:97], v[4:19]
	ds_read2_b64 v[94:97], v85 offset0:56 offset1:58
	s_waitcnt lgkmcnt(3)
	v_mfma_f32_32x32x16_bf16 v[4:19], v[60:63], v[98:101], v[4:19]
	ds_read2_b64 v[98:101], v85 offset0:60 offset1:62
	s_waitcnt lgkmcnt(3)
	v_mfma_f32_32x32x16_bf16 v[4:19], v[68:71], v[102:105], v[4:19]
	s_waitcnt lgkmcnt(2)
	v_mfma_f32_32x32x16_bf16 v[4:19], v[72:75], v[86:89], v[4:19]
	s_waitcnt lgkmcnt(1)
	v_mfma_f32_32x32x16_bf16 v[4:19], v[76:79], v[94:97], v[4:19]
	s_waitcnt lgkmcnt(0)
	v_mfma_f32_32x32x16_bf16 v[4:19], v[80:83], v[98:101], v[4:19]
	s_nop 11
	v_cvt_pk_bf16_f32 v4, v4, v5
	ds_write_b16 v84, v4 offset:128
	ds_write_b16_d16_hi v84, v4 offset:400
	v_cvt_pk_bf16_f32 v4, v6, v7
	ds_write_b16 v84, v4 offset:672
	ds_write_b16_d16_hi v84, v4 offset:944
	v_cvt_pk_bf16_f32 v4, v8, v9
	ds_write_b16 v84, v4 offset:2304
	ds_write_b16_d16_hi v84, v4 offset:2576
	v_cvt_pk_bf16_f32 v4, v10, v11
	ds_write_b16 v84, v4 offset:2848
	ds_write_b16_d16_hi v84, v4 offset:3120
	v_cvt_pk_bf16_f32 v4, v12, v13
	ds_write_b16 v84, v4 offset:4480
	ds_write_b16_d16_hi v84, v4 offset:4752
	v_cvt_pk_bf16_f32 v4, v14, v15
	ds_write_b16 v84, v4 offset:5024
	ds_write_b16_d16_hi v84, v4 offset:5296
	v_cvt_pk_bf16_f32 v4, v16, v17
	ds_write_b16 v84, v4 offset:6656
	ds_write_b16_d16_hi v84, v4 offset:6928
	v_cvt_pk_bf16_f32 v4, v18, v19
	ds_write_b16 v84, v4 offset:7200
	ds_write_b16_d16_hi v84, v4 offset:7472
	v_mad_u32_u24 v85, v212, s8, v92
	ds_read2_b64 v[4:7], v85 offset1:2
	ds_read2_b64 v[86:89], v85 offset0:4 offset1:6
	ds_read2_b64 v[94:97], v85 offset0:8 offset1:10
	ds_read2_b64 v[98:101], v85 offset0:12 offset1:14
	ds_read2_b64 v[102:105], v85 offset0:16 offset1:18
	s_waitcnt lgkmcnt(4)
	v_mfma_f32_32x32x16_bf16 v[4:19], v[20:23], v[4:7], 0
	s_waitcnt lgkmcnt(3)
	v_mfma_f32_32x32x16_bf16 v[4:19], v[24:27], v[86:89], v[4:19]
	ds_read2_b64 v[86:89], v85 offset0:20 offset1:22
	s_waitcnt lgkmcnt(3)
	v_mfma_f32_32x32x16_bf16 v[4:19], v[32:35], v[94:97], v[4:19]
	ds_read2_b64 v[94:97], v85 offset0:24 offset1:26
	s_waitcnt lgkmcnt(3)
	v_mfma_f32_32x32x16_bf16 v[4:19], v[28:31], v[98:101], v[4:19]
	ds_read2_b64 v[98:101], v85 offset0:28 offset1:30
	s_waitcnt lgkmcnt(3)
	v_mfma_f32_32x32x16_bf16 v[4:19], v[36:39], v[102:105], v[4:19]
	ds_read2_b64 v[102:105], v85 offset0:32 offset1:34
	s_waitcnt lgkmcnt(3)
	v_mfma_f32_32x32x16_bf16 v[4:19], v[40:43], v[86:89], v[4:19]
	ds_read2_b64 v[86:89], v85 offset0:36 offset1:38
	s_waitcnt lgkmcnt(3)
	v_mfma_f32_32x32x16_bf16 v[4:19], v[48:51], v[94:97], v[4:19]
	ds_read2_b64 v[94:97], v85 offset0:40 offset1:42
	s_waitcnt lgkmcnt(3)
	v_mfma_f32_32x32x16_bf16 v[4:19], v[44:47], v[98:101], v[4:19]
	ds_read2_b64 v[98:101], v85 offset0:44 offset1:46
	s_waitcnt lgkmcnt(3)
	v_mfma_f32_32x32x16_bf16 v[4:19], v[52:55], v[102:105], v[4:19]
	ds_read2_b64 v[102:105], v85 offset0:48 offset1:50
	s_waitcnt lgkmcnt(3)
	v_mfma_f32_32x32x16_bf16 v[4:19], v[56:59], v[86:89], v[4:19]
	ds_read2_b64 v[86:89], v85 offset0:52 offset1:54
	s_waitcnt lgkmcnt(3)
	v_mfma_f32_32x32x16_bf16 v[4:19], v[64:67], v[94:97], v[4:19]
	ds_read2_b64 v[94:97], v85 offset0:56 offset1:58
	s_waitcnt lgkmcnt(3)
	v_mfma_f32_32x32x16_bf16 v[4:19], v[60:63], v[98:101], v[4:19]
	ds_read2_b64 v[98:101], v85 offset0:60 offset1:62
	s_waitcnt lgkmcnt(3)
	v_mfma_f32_32x32x16_bf16 v[4:19], v[68:71], v[102:105], v[4:19]
	s_waitcnt lgkmcnt(2)
	v_mfma_f32_32x32x16_bf16 v[4:19], v[72:75], v[86:89], v[4:19]
	s_waitcnt lgkmcnt(1)
	v_mfma_f32_32x32x16_bf16 v[4:19], v[76:79], v[94:97], v[4:19]
	s_waitcnt lgkmcnt(0)
	v_mfma_f32_32x32x16_bf16 v[4:19], v[80:83], v[98:101], v[4:19]
	s_nop 11
	v_cvt_pk_bf16_f32 v4, v4, v5
	ds_write_b16 v84, v4 offset:192
	ds_write_b16_d16_hi v84, v4 offset:464
	v_cvt_pk_bf16_f32 v4, v6, v7
	ds_write_b16 v84, v4 offset:736
	ds_write_b16_d16_hi v84, v4 offset:1008
	v_cvt_pk_bf16_f32 v4, v8, v9
	ds_write_b16 v84, v4 offset:2368
	ds_write_b16_d16_hi v84, v4 offset:2640
	v_cvt_pk_bf16_f32 v4, v10, v11
	ds_write_b16 v84, v4 offset:2912
	ds_write_b16_d16_hi v84, v4 offset:3184
	v_cvt_pk_bf16_f32 v4, v12, v13
	ds_write_b16 v84, v4 offset:4544
	ds_write_b16_d16_hi v84, v4 offset:4816
	v_cvt_pk_bf16_f32 v4, v14, v15
	ds_write_b16 v84, v4 offset:5088
	ds_write_b16_d16_hi v84, v4 offset:5360
	v_cvt_pk_bf16_f32 v4, v16, v17
	ds_write_b16 v84, v4 offset:6720
	ds_write_b16_d16_hi v84, v4 offset:6992
	v_cvt_pk_bf16_f32 v4, v18, v19
	ds_write_b16 v84, v4 offset:7264
	ds_write_b16_d16_hi v84, v4 offset:7536
	v_mul_u32_u24_e32 v4, 0x110, v210
	v_add3_u32 v6, s61, v4, v2
	ds_read_b128 v[8:11], v6
	s_mulk_i32 s41, 0xc00
	s_mul_hi_u32 s44, s40, 0xc00
	s_waitcnt vmcnt(7)
	v_lshlrev_b32_e32 v14, 16, v160
	v_and_b32_e32 v15, 0xffff0000, v160
	s_waitcnt lgkmcnt(0)
	v_lshlrev_b32_e32 v12, 16, v8
	v_and_b32_e32 v13, 0xffff0000, v8
	s_add_i32 s44, s44, s41
	s_mulk_i32 s40, 0xc00
	v_pk_mul_f32 v[12:13], v[14:15], v[12:13]
	s_add_u32 s40, s36, s40
	v_cvt_pk_bf16_f32 v8, v12, v13
	v_lshlrev_b32_e32 v12, 16, v9
	v_and_b32_e32 v13, 0xffff0000, v9
	v_lshlrev_b32_e32 v14, 16, v161
	v_and_b32_e32 v15, 0xffff0000, v161
	s_addc_u32 s41, s37, s44
	v_pk_mul_f32 v[12:13], v[14:15], v[12:13]
	s_add_u32 s40, s40, s24
	v_mul_u32_u24_e32 v4, 0x600, v210
	v_cvt_pk_bf16_f32 v9, v12, v13
	v_lshlrev_b32_e32 v12, 16, v10
	v_and_b32_e32 v13, 0xffff0000, v10
	v_lshlrev_b32_e32 v14, 16, v162
	v_and_b32_e32 v15, 0xffff0000, v162
	s_addc_u32 s41, s41, 0
	v_lshlrev_b32_e32 v4, 1, v4
	v_mov_b32_e32 v5, v3
	v_pk_mul_f32 v[12:13], v[14:15], v[12:13]
	v_lshl_add_u64 v[4:5], s[40:41], 0, v[4:5]
	v_cvt_pk_bf16_f32 v10, v12, v13
	v_lshlrev_b32_e32 v12, 16, v11
	v_and_b32_e32 v13, 0xffff0000, v11
	v_lshlrev_b32_e32 v14, 16, v163
	v_and_b32_e32 v15, 0xffff0000, v163
	v_lshl_add_u64 v[4:5], v[4:5], 0, v[2:3]
	v_pk_mul_f32 v[12:13], v[14:15], v[12:13]
	s_waitcnt vmcnt(6)
	v_lshlrev_b32_e32 v14, 16, v156
	v_cvt_pk_bf16_f32 v11, v12, v13
	v_add_co_u32_e32 v12, vcc, s21, v4
	v_and_b32_e32 v15, 0xffff0000, v156
	s_nop 0
	v_addc_co_u32_e32 v13, vcc, 0, v5, vcc
	global_store_dwordx4 v[12:13], v[8:11], off offset:2048 sc1
	ds_read_b128 v[8:11], v6 offset:1088
	s_add_i32 s43, s43, s10
	s_add_i32 s42, s42, s93
	s_add_i32 s14, s14, s29
	s_cmpk_lt_i32 s43, 0x100
	s_waitcnt lgkmcnt(0)
	v_lshlrev_b32_e32 v12, 16, v8
	v_and_b32_e32 v13, 0xffff0000, v8
	v_pk_mul_f32 v[12:13], v[14:15], v[12:13]
	v_lshlrev_b32_e32 v14, 16, v157
	v_cvt_pk_bf16_f32 v8, v12, v13
	v_lshlrev_b32_e32 v12, 16, v9
	v_and_b32_e32 v13, 0xffff0000, v9
	v_and_b32_e32 v15, 0xffff0000, v157
	v_pk_mul_f32 v[12:13], v[14:15], v[12:13]
	v_lshlrev_b32_e32 v14, 16, v158
	v_cvt_pk_bf16_f32 v9, v12, v13
	v_lshlrev_b32_e32 v12, 16, v10
	v_and_b32_e32 v13, 0xffff0000, v10
	v_and_b32_e32 v15, 0xffff0000, v158
	v_pk_mul_f32 v[12:13], v[14:15], v[12:13]
	v_lshlrev_b32_e32 v14, 16, v159
	v_cvt_pk_bf16_f32 v10, v12, v13
	v_lshlrev_b32_e32 v12, 16, v11
	v_and_b32_e32 v13, 0xffff0000, v11
	v_and_b32_e32 v15, 0xffff0000, v159
	v_pk_mul_f32 v[12:13], v[14:15], v[12:13]
	s_waitcnt vmcnt(6)
	v_lshlrev_b32_e32 v14, 16, v152
	v_cvt_pk_bf16_f32 v11, v12, v13
	v_add_co_u32_e32 v12, vcc, s2, v4
	v_and_b32_e32 v15, 0xffff0000, v152
	s_nop 0
	v_addc_co_u32_e32 v13, vcc, 0, v5, vcc
	global_store_dwordx4 v[12:13], v[8:11], off offset:2048 sc1
	ds_read_b128 v[8:11], v6 offset:2176
	s_waitcnt lgkmcnt(0)
	v_lshlrev_b32_e32 v12, 16, v8
	v_and_b32_e32 v13, 0xffff0000, v8
	v_pk_mul_f32 v[12:13], v[14:15], v[12:13]
	v_lshlrev_b32_e32 v14, 16, v153
	v_cvt_pk_bf16_f32 v8, v12, v13
	v_lshlrev_b32_e32 v12, 16, v9
	v_and_b32_e32 v13, 0xffff0000, v9
	v_and_b32_e32 v15, 0xffff0000, v153
	v_pk_mul_f32 v[12:13], v[14:15], v[12:13]
	v_lshlrev_b32_e32 v14, 16, v154
	v_cvt_pk_bf16_f32 v9, v12, v13
	v_lshlrev_b32_e32 v12, 16, v10
	v_and_b32_e32 v13, 0xffff0000, v10
	v_and_b32_e32 v15, 0xffff0000, v154
	v_pk_mul_f32 v[12:13], v[14:15], v[12:13]
	v_lshlrev_b32_e32 v14, 16, v155
	v_cvt_pk_bf16_f32 v10, v12, v13
	v_lshlrev_b32_e32 v12, 16, v11
	v_and_b32_e32 v13, 0xffff0000, v11
	v_and_b32_e32 v15, 0xffff0000, v155
	v_pk_mul_f32 v[12:13], v[14:15], v[12:13]
	s_waitcnt vmcnt(6)
	v_lshlrev_b32_e32 v14, 16, v148
	v_cvt_pk_bf16_f32 v11, v12, v13
	v_add_co_u32_e32 v12, vcc, s3, v4
	v_and_b32_e32 v15, 0xffff0000, v148
	s_nop 0
	v_addc_co_u32_e32 v13, vcc, 0, v5, vcc
	global_store_dwordx4 v[12:13], v[8:11], off offset:2048 sc1
	ds_read_b128 v[8:11], v6 offset:3264
	s_waitcnt lgkmcnt(0)
	v_lshlrev_b32_e32 v12, 16, v8
	v_and_b32_e32 v13, 0xffff0000, v8
	v_pk_mul_f32 v[12:13], v[14:15], v[12:13]
	v_lshlrev_b32_e32 v14, 16, v149
	v_cvt_pk_bf16_f32 v8, v12, v13
	v_lshlrev_b32_e32 v12, 16, v9
	v_and_b32_e32 v13, 0xffff0000, v9
	v_and_b32_e32 v15, 0xffff0000, v149
	v_pk_mul_f32 v[12:13], v[14:15], v[12:13]
	v_lshlrev_b32_e32 v14, 16, v150
	v_cvt_pk_bf16_f32 v9, v12, v13
	v_lshlrev_b32_e32 v12, 16, v10
	v_and_b32_e32 v13, 0xffff0000, v10
	v_and_b32_e32 v15, 0xffff0000, v150
	v_pk_mul_f32 v[12:13], v[14:15], v[12:13]
	v_lshlrev_b32_e32 v14, 16, v151
	v_cvt_pk_bf16_f32 v10, v12, v13
	v_lshlrev_b32_e32 v12, 16, v11
	v_and_b32_e32 v13, 0xffff0000, v11
	v_and_b32_e32 v15, 0xffff0000, v151
	v_pk_mul_f32 v[12:13], v[14:15], v[12:13]
	s_waitcnt vmcnt(6)
	v_lshlrev_b32_e32 v14, 16, v144
	v_cvt_pk_bf16_f32 v11, v12, v13
	v_add_co_u32_e32 v12, vcc, s94, v4
	v_and_b32_e32 v15, 0xffff0000, v144
	s_nop 0
	v_addc_co_u32_e32 v13, vcc, 0, v5, vcc
	global_store_dwordx4 v[12:13], v[8:11], off offset:2048 sc1
	ds_read_b128 v[8:11], v6 offset:4352
	s_waitcnt lgkmcnt(0)
	v_lshlrev_b32_e32 v12, 16, v8
	v_and_b32_e32 v13, 0xffff0000, v8
	v_pk_mul_f32 v[12:13], v[14:15], v[12:13]
	v_lshlrev_b32_e32 v14, 16, v145
	v_cvt_pk_bf16_f32 v8, v12, v13
	v_lshlrev_b32_e32 v12, 16, v9
	v_and_b32_e32 v13, 0xffff0000, v9
	v_and_b32_e32 v15, 0xffff0000, v145
	v_pk_mul_f32 v[12:13], v[14:15], v[12:13]
	v_lshlrev_b32_e32 v14, 16, v146
	v_cvt_pk_bf16_f32 v9, v12, v13
	v_lshlrev_b32_e32 v12, 16, v10
	v_and_b32_e32 v13, 0xffff0000, v10
	v_and_b32_e32 v15, 0xffff0000, v146
	v_pk_mul_f32 v[12:13], v[14:15], v[12:13]
	v_lshlrev_b32_e32 v14, 16, v147
	v_cvt_pk_bf16_f32 v10, v12, v13
	v_lshlrev_b32_e32 v12, 16, v11
	v_and_b32_e32 v13, 0xffff0000, v11
	v_and_b32_e32 v15, 0xffff0000, v147
	v_pk_mul_f32 v[12:13], v[14:15], v[12:13]
	s_waitcnt vmcnt(6)
	v_lshlrev_b32_e32 v14, 16, v140
	v_cvt_pk_bf16_f32 v11, v12, v13
	v_add_co_u32_e32 v12, vcc, s97, v4
	v_and_b32_e32 v15, 0xffff0000, v140
	s_nop 0
	v_addc_co_u32_e32 v13, vcc, 0, v5, vcc
	global_store_dwordx4 v[12:13], v[8:11], off offset:2048 sc1
	ds_read_b128 v[8:11], v6 offset:5440
	s_waitcnt lgkmcnt(0)
	v_lshlrev_b32_e32 v12, 16, v8
	v_and_b32_e32 v13, 0xffff0000, v8
	v_pk_mul_f32 v[12:13], v[14:15], v[12:13]
	v_lshlrev_b32_e32 v14, 16, v141
	v_cvt_pk_bf16_f32 v8, v12, v13
	v_lshlrev_b32_e32 v12, 16, v9
	v_and_b32_e32 v13, 0xffff0000, v9
	v_and_b32_e32 v15, 0xffff0000, v141
	v_pk_mul_f32 v[12:13], v[14:15], v[12:13]
	v_lshlrev_b32_e32 v14, 16, v142
	v_cvt_pk_bf16_f32 v9, v12, v13
	v_lshlrev_b32_e32 v12, 16, v10
	v_and_b32_e32 v13, 0xffff0000, v10
	v_and_b32_e32 v15, 0xffff0000, v142
	v_pk_mul_f32 v[12:13], v[14:15], v[12:13]
	v_lshlrev_b32_e32 v14, 16, v143
	v_cvt_pk_bf16_f32 v10, v12, v13
	v_lshlrev_b32_e32 v12, 16, v11
	v_and_b32_e32 v13, 0xffff0000, v11
	v_and_b32_e32 v15, 0xffff0000, v143
	v_pk_mul_f32 v[12:13], v[14:15], v[12:13]
	s_waitcnt vmcnt(6)
	v_lshlrev_b32_e32 v14, 16, v136
	v_cvt_pk_bf16_f32 v11, v12, v13
	v_add_co_u32_e32 v12, vcc, s4, v4
	v_and_b32_e32 v15, 0xffff0000, v136
	s_nop 0
	v_addc_co_u32_e32 v13, vcc, 0, v5, vcc
	global_store_dwordx4 v[12:13], v[8:11], off offset:2048 sc1
	ds_read_b128 v[8:11], v6 offset:6528
	s_waitcnt lgkmcnt(0)
	v_lshlrev_b32_e32 v12, 16, v8
	v_and_b32_e32 v13, 0xffff0000, v8
	v_pk_mul_f32 v[12:13], v[14:15], v[12:13]
	v_lshlrev_b32_e32 v14, 16, v137
	v_cvt_pk_bf16_f32 v8, v12, v13
	v_lshlrev_b32_e32 v12, 16, v9
	v_and_b32_e32 v13, 0xffff0000, v9
	v_and_b32_e32 v15, 0xffff0000, v137
	v_pk_mul_f32 v[12:13], v[14:15], v[12:13]
	v_lshlrev_b32_e32 v14, 16, v138
	v_cvt_pk_bf16_f32 v9, v12, v13
	v_lshlrev_b32_e32 v12, 16, v10
	v_and_b32_e32 v13, 0xffff0000, v10
	v_and_b32_e32 v15, 0xffff0000, v138
	v_pk_mul_f32 v[12:13], v[14:15], v[12:13]
	v_lshlrev_b32_e32 v14, 16, v139
	v_cvt_pk_bf16_f32 v10, v12, v13
	v_lshlrev_b32_e32 v12, 16, v11
	v_and_b32_e32 v13, 0xffff0000, v11
	v_and_b32_e32 v15, 0xffff0000, v139
	v_pk_mul_f32 v[12:13], v[14:15], v[12:13]
	s_nop 0
	v_cvt_pk_bf16_f32 v11, v12, v13
	v_add_co_u32_e32 v12, vcc, s22, v4
	s_nop 1
	v_addc_co_u32_e32 v13, vcc, 0, v5, vcc
	global_store_dwordx4 v[12:13], v[8:11], off offset:2048 sc1
	ds_read_b128 v[6:9], v6 offset:7616
	s_waitcnt vmcnt(7)
	v_lshlrev_b32_e32 v12, 16, v132
	v_and_b32_e32 v13, 0xffff0000, v132
	v_add_co_u32_e32 v4, vcc, 0xc615000, v4
	s_waitcnt lgkmcnt(0)
	v_lshlrev_b32_e32 v10, 16, v6
	v_and_b32_e32 v11, 0xffff0000, v6
	v_pk_mul_f32 v[10:11], v[12:13], v[10:11]
	v_lshlrev_b32_e32 v12, 16, v133
	v_cvt_pk_bf16_f32 v6, v10, v11
	v_lshlrev_b32_e32 v10, 16, v7
	v_and_b32_e32 v11, 0xffff0000, v7
	v_and_b32_e32 v13, 0xffff0000, v133
	v_pk_mul_f32 v[10:11], v[12:13], v[10:11]
	v_lshlrev_b32_e32 v12, 16, v134
	v_cvt_pk_bf16_f32 v7, v10, v11
	v_lshlrev_b32_e32 v10, 16, v8
	v_and_b32_e32 v11, 0xffff0000, v8
	v_and_b32_e32 v13, 0xffff0000, v134
	v_pk_mul_f32 v[10:11], v[12:13], v[10:11]
	v_lshlrev_b32_e32 v12, 16, v135
	v_cvt_pk_bf16_f32 v8, v10, v11
	v_lshlrev_b32_e32 v10, 16, v9
	v_and_b32_e32 v11, 0xffff0000, v9
	v_and_b32_e32 v13, 0xffff0000, v135
	v_pk_mul_f32 v[10:11], v[12:13], v[10:11]
	v_addc_co_u32_e32 v5, vcc, 0, v5, vcc
	v_cvt_pk_bf16_f32 v9, v10, v11
	global_store_dwordx4 v[4:5], v[6:9], off offset:2048 sc1
	s_barrier
	s_cbranch_scc1 .LBB0_758
	s_branch .LBB0_681
